# code placement: every MFMA segment starts at 4 mod 8 bytes (on top of moved flips)
# baseline (speedup 1.0000x reference)
; #define PG8_STAGE(bufoff, gbase, voff) do { _Pragma("unroll") for (int _i = 0; _i < 2; ++_i) \
;         __builtin_amdgcn_global_load_lds((const unsigned*)((const char*)(gbase) + (voff)[_i]), (LAS unsigned*)(lds + (bufoff) + ldsw + _i * 8192), 16, 0, 0); } while (0)
; #define PG8_LDA(dst, b, h) do { _Pragma("unroll") for (int m = 0; m < 4; ++m) _Pragma("unroll") for (int k = 0; k < 2; ++k) dst[m][k] = *(const LAS bf16x8*)(lds + PG8_SA(b, h) + aoff + m * 2048 + k * 1024); } while (0)
; #define PG8_LDB(dst, b, h) do { _Pragma("unroll") for (int n = 0; n < 2; ++n) _Pragma("unroll") for (int k = 0; k < 2; ++k) dst[n][k] = *(const LAS bf16x8*)(lds + PG8_SB(b, h) + boff + n * 2048 + k * 1024); } while (0)
; #define PG8_MMA(ai, bj, At, Bt) do { __builtin_amdgcn_s_setprio(1); _Pragma("unroll") for (int m = 0; m < 4; ++m) _Pragma("unroll") for (int n = 0; n < 2; ++n) _Pragma("unroll") for (int k = 0; k < 2; ++k) \
;         acc[ai][bj][m][n] = __builtin_amdgcn_mfma_f32_16x16x32_bf16(Bt[n][k], At[m][k], acc[ai][bj][m][n], 0, 0, 0); __builtin_amdgcn_s_setprio(0); } while (0)
; #define PG8_WAIT_V(n) asm volatile("s_waitcnt vmcnt(" #n ")" ::: "memory")
; #define PG8_WAIT_L(n) asm volatile("s_waitcnt lgkmcnt(" #n ")" ::: "memory")
; #define PG8_BAR __builtin_amdgcn_s_barrier()
; #define PG8_SCHED __builtin_amdgcn_sched_barrier(0)
; template <class Epi, bool ALIGN_EPI, bool SP2 = PG8_SP2_DEFAULT>
; __device__ __forceinline__ void gemm_phase(LAS unsigned char* lds, const Gemm g, const StaticOrder& S, const Epi& E) {
;     ...
;             const bool last = (t == nt - 2);
;             const char* a1 = cA + (size_t)(t + 1) * kstep;
;             const char* a2 = last ? nA : cA + (size_t)(t + 2) * kstep; const char* b2 = last ? nB : cB + (size_t)(t + 2) * kstep;
;             const char* a3 = a2 + kstep; const char* b3 = b2 + kstep;
;             if constexpr (SP2) {
;             PG8_LDB(B0, 0, 0); PG8_LDB(B1, 0, 1); PG8_SCHED; PG8_LDA(At, 0, 0); PG8_STAGE(PG8_SA(1, 1), a1 + hstepA, voffA);
;             PG8_WAIT_V(8); PG8_WAIT_L(0); PG8_BAR; PG8_MMA(0, 0, At, B0); PG8_MMA(0, 1, At, B1); PG8_BAR; PG8_SCHED;
;             PG8_LDA(At, 0, 1); PG8_STAGE(PG8_SB(0, 0), b2, voffB); PG8_STAGE(PG8_SB(0, 1), b2 + hstepB, voffB); PG8_STAGE(PG8_SA(0, 0), a2, voffA);
.LBB0_250:
	ds_read_b128 v[150:153], v147
	ds_read_b128 v[154:157], v147 offset:1024
	ds_read_b128 v[158:161], v147 offset:2048
	ds_read_b128 v[162:165], v147 offset:3072
	ds_read_b128 v[166:169], v148
	ds_read_b128 v[170:173], v148 offset:1024
	ds_read_b128 v[174:177], v148 offset:2048
	ds_read_b128 v[178:181], v148 offset:3072
	s_add_u32 s20, s18, 0xfff00080
	s_addc_u32 s21, s19, -1
	s_cmp_eq_u32 s44, 60
	s_cselect_b32 s23, s13, s21
	s_cselect_b32 s22, s40, s20
	s_cselect_b32 s21, s11, s43
	s_cselect_b32 s20, s41, s42
	v_lshl_add_u64 v[206:207], s[18:19], 0, v[136:137]
	s_add_i32 m0, s9, 0xc000
	ds_read_b128 v[182:185], v149
	ds_read_b128 v[186:189], v149 offset:1024
	ds_read_b128 v[190:193], v149 offset:2048
	ds_read_b128 v[198:201], v149 offset:3072
	ds_read_b128 v[202:205], v149 offset:4096
	ds_read_b128 v[216:219], v149 offset:5120
	ds_read_b128 v[220:223], v149 offset:6144
	ds_read_b128 v[224:227], v149 offset:7168
	global_load_lds_dwordx4 v[206:207], off
	v_lshl_add_u64 v[206:207], s[18:19], 0, v[138:139]
	s_add_i32 m0, s9, 0xe000
	s_nop 0
	global_load_lds_dwordx4 v[206:207], off
	s_nop 0
	s_waitcnt vmcnt(8)
	s_waitcnt lgkmcnt(0)
	s_setprio 1
	s_barrier
	v_mfma_f32_16x16x32_bf16 v[124:127], v[150:153], v[182:185], v[124:127]
	v_mfma_f32_16x16x32_bf16 v[120:123], v[158:161], v[182:185], v[120:123]
	v_mfma_f32_16x16x32_bf16 v[116:119], v[150:153], v[190:193], v[116:119]
	v_mfma_f32_16x16x32_bf16 v[112:115], v[158:161], v[190:193], v[112:115]
	v_mfma_f32_16x16x32_bf16 v[100:103], v[150:153], v[202:205], v[100:103]
	v_mfma_f32_16x16x32_bf16 v[96:99], v[158:161], v[202:205], v[96:99]
	v_mfma_f32_16x16x32_bf16 v[84:87], v[150:153], v[220:223], v[84:87]
	v_mfma_f32_16x16x32_bf16 v[80:83], v[158:161], v[220:223], v[80:83]
	v_mfma_f32_16x16x32_bf16 v[124:127], v[154:157], v[186:189], v[124:127]
	v_mfma_f32_16x16x32_bf16 v[120:123], v[162:165], v[186:189], v[120:123]
	v_mfma_f32_16x16x32_bf16 v[116:119], v[154:157], v[198:201], v[116:119]
	v_mfma_f32_16x16x32_bf16 v[112:115], v[162:165], v[198:201], v[112:115]
	v_mfma_f32_16x16x32_bf16 v[100:103], v[154:157], v[216:219], v[100:103]
	v_mfma_f32_16x16x32_bf16 v[96:99], v[162:165], v[216:219], v[96:99]
	v_mfma_f32_16x16x32_bf16 v[84:87], v[154:157], v[224:227], v[84:87]
	v_mfma_f32_16x16x32_bf16 v[80:83], v[162:165], v[224:227], v[80:83]
	v_mfma_f32_16x16x32_bf16 v[108:111], v[166:169], v[182:185], v[108:111]
	v_mfma_f32_16x16x32_bf16 v[104:107], v[174:177], v[182:185], v[104:107]
	v_mfma_f32_16x16x32_bf16 v[92:95], v[166:169], v[190:193], v[92:95]
	v_mfma_f32_16x16x32_bf16 v[88:91], v[174:177], v[190:193], v[88:91]
	v_mfma_f32_16x16x32_bf16 v[76:79], v[166:169], v[202:205], v[76:79]
	v_mfma_f32_16x16x32_bf16 v[72:75], v[174:177], v[202:205], v[72:75]
	v_mfma_f32_16x16x32_bf16 v[68:71], v[166:169], v[220:223], v[68:71]
	v_mfma_f32_16x16x32_bf16 v[64:67], v[174:177], v[220:223], v[64:67]
	v_mfma_f32_16x16x32_bf16 v[108:111], v[170:173], v[186:189], v[108:111]
	v_mfma_f32_16x16x32_bf16 v[104:107], v[178:181], v[186:189], v[104:107]
	v_mfma_f32_16x16x32_bf16 v[92:95], v[170:173], v[198:201], v[92:95]
	v_mfma_f32_16x16x32_bf16 v[88:91], v[178:181], v[198:201], v[88:91]
	v_mfma_f32_16x16x32_bf16 v[76:79], v[170:173], v[216:219], v[76:79]
	v_mfma_f32_16x16x32_bf16 v[72:75], v[178:181], v[216:219], v[72:75]
	v_mfma_f32_16x16x32_bf16 v[68:71], v[170:173], v[224:227], v[68:71]
	v_mfma_f32_16x16x32_bf16 v[64:67], v[178:181], v[224:227], v[64:67]
	s_barrier
	s_setprio 0
	s_add_i32 s45, s36, s24
	v_lshl_add_u64 v[206:207], s[20:21], 0, v[132:133]
	s_mov_b32 m0, s45
	ds_read_b128 v[182:185], v149 offset:16384
	ds_read_b128 v[186:189], v149 offset:17408
	ds_read_b128 v[190:193], v149 offset:18432
	ds_read_b128 v[198:201], v149 offset:19456
	ds_read_b128 v[202:205], v149 offset:20480
	ds_read_b128 v[216:219], v149 offset:21504
	ds_read_b128 v[220:223], v149 offset:22528
	ds_read_b128 v[224:227], v149 offset:23552
	global_load_lds_dwordx4 v[206:207], off
	s_add_i32 m0, s45, 0x2000
	s_add_u32 s46, s20, 0x100000
	v_lshl_add_u64 v[210:211], s[20:21], 0, v[128:129]
	s_addc_u32 s47, s21, 0
	s_add_i32 s45, s37, s24
	global_load_lds_dwordx4 v[210:211], off
	v_lshl_add_u64 v[228:229], s[46:47], 0, v[132:133]
	s_mov_b32 m0, s45
	v_lshl_add_u64 v[230:231], s[22:23], 0, v[130:131]
	global_load_lds_dwordx4 v[228:229], off
	v_lshl_add_u64 v[228:229], s[46:47], 0, v[128:129]
	s_add_i32 m0, s45, 0x2000
	s_nop 0
	global_load_lds_dwordx4 v[228:229], off
	v_lshl_add_u64 v[228:229], s[22:23], 0, v[134:135]
	s_mov_b32 m0, s9
	s_nop 0
	global_load_lds_dwordx4 v[228:229], off
	s_mov_b32 m0, s27
	s_nop 0
	global_load_lds_dwordx4 v[230:231], off
	s_waitcnt vmcnt(8)
	s_waitcnt lgkmcnt(0)
	s_setprio 1
	s_barrier
; #define PG8_STAGE(bufoff, gbase, voff) do { _Pragma("unroll") for (int _i = 0; _i < 2; ++_i) \
;         __builtin_amdgcn_global_load_lds((const unsigned*)((const char*)(gbase) + (voff)[_i]), (LAS unsigned*)(lds + (bufoff) + ldsw + _i * 8192), 16, 0, 0); } while (0)
; #define PG8_LDA(dst, b, h) do { _Pragma("unroll") for (int m = 0; m < 4; ++m) _Pragma("unroll") for (int k = 0; k < 2; ++k) dst[m][k] = *(const LAS bf16x8*)(lds + PG8_SA(b, h) + aoff + m * 2048 + k * 1024); } while (0)
; #define PG8_LDB(dst, b, h) do { _Pragma("unroll") for (int n = 0; n < 2; ++n) _Pragma("unroll") for (int k = 0; k < 2; ++k) dst[n][k] = *(const LAS bf16x8*)(lds + PG8_SB(b, h) + boff + n * 2048 + k * 1024); } while (0)
; #define PG8_MMA(ai, bj, At, Bt) do { __builtin_amdgcn_s_setprio(1); _Pragma("unroll") for (int m = 0; m < 4; ++m) _Pragma("unroll") for (int n = 0; n < 2; ++n) _Pragma("unroll") for (int k = 0; k < 2; ++k) \
;         acc[ai][bj][m][n] = __builtin_amdgcn_mfma_f32_16x16x32_bf16(Bt[n][k], At[m][k], acc[ai][bj][m][n], 0, 0, 0); __builtin_amdgcn_s_setprio(0); } while (0)
; #define PG8_WAIT_V(n) asm volatile("s_waitcnt vmcnt(" #n ")" ::: "memory")
; #define PG8_WAIT_L(n) asm volatile("s_waitcnt lgkmcnt(" #n ")" ::: "memory")
; #define PG8_BAR __builtin_amdgcn_s_barrier()
; #define PG8_SCHED __builtin_amdgcn_sched_barrier(0)
; template <class Epi, bool ALIGN_EPI, bool SP2 = PG8_SP2_DEFAULT>
; __device__ __forceinline__ void gemm_phase(LAS unsigned char* lds, const Gemm g, const StaticOrder& S, const Epi& E) {
;     ...
;             PG8_WAIT_V(8); PG8_WAIT_L(0); PG8_BAR; PG8_MMA(1, 0, At, B0); PG8_MMA(1, 1, At, B1); PG8_BAR; PG8_SCHED;
;             PG8_LDB(B0, 1, 0); PG8_LDB(B1, 1, 1); PG8_SCHED; PG8_LDA(At, 1, 0); PG8_STAGE(PG8_SA(0, 1), a2 + hstepA, voffA);
;             PG8_WAIT_V(8); PG8_WAIT_L(0); PG8_BAR; PG8_MMA(0, 0, At, B0); PG8_MMA(0, 1, At, B1); PG8_BAR; PG8_SCHED;
	v_mfma_f32_16x16x32_bf16 v[60:63], v[150:153], v[182:185], v[60:63]
	v_mfma_f32_16x16x32_bf16 v[56:59], v[158:161], v[182:185], v[56:59]
	v_mfma_f32_16x16x32_bf16 v[52:55], v[150:153], v[190:193], v[52:55]
	v_mfma_f32_16x16x32_bf16 v[48:51], v[158:161], v[190:193], v[48:51]
	v_mfma_f32_16x16x32_bf16 v[36:39], v[150:153], v[202:205], v[36:39]
	v_mfma_f32_16x16x32_bf16 v[32:35], v[158:161], v[202:205], v[32:35]
	v_mfma_f32_16x16x32_bf16 v[20:23], v[150:153], v[220:223], v[20:23]
	v_mfma_f32_16x16x32_bf16 v[16:19], v[158:161], v[220:223], v[16:19]
	v_mfma_f32_16x16x32_bf16 v[60:63], v[154:157], v[186:189], v[60:63]
	v_mfma_f32_16x16x32_bf16 v[56:59], v[162:165], v[186:189], v[56:59]
	v_mfma_f32_16x16x32_bf16 v[52:55], v[154:157], v[198:201], v[52:55]
	v_mfma_f32_16x16x32_bf16 v[48:51], v[162:165], v[198:201], v[48:51]
	v_mfma_f32_16x16x32_bf16 v[36:39], v[154:157], v[216:219], v[36:39]
	v_mfma_f32_16x16x32_bf16 v[32:35], v[162:165], v[216:219], v[32:35]
	v_mfma_f32_16x16x32_bf16 v[20:23], v[154:157], v[224:227], v[20:23]
	v_mfma_f32_16x16x32_bf16 v[16:19], v[162:165], v[224:227], v[16:19]
	v_mfma_f32_16x16x32_bf16 v[44:47], v[166:169], v[182:185], v[44:47]
	v_mfma_f32_16x16x32_bf16 v[40:43], v[174:177], v[182:185], v[40:43]
	v_mfma_f32_16x16x32_bf16 v[28:31], v[166:169], v[190:193], v[28:31]
	v_mfma_f32_16x16x32_bf16 v[24:27], v[174:177], v[190:193], v[24:27]
	v_mfma_f32_16x16x32_bf16 v[12:15], v[166:169], v[202:205], v[12:15]
	v_mfma_f32_16x16x32_bf16 v[8:11], v[174:177], v[202:205], v[8:11]
	v_mfma_f32_16x16x32_bf16 v[4:7], v[166:169], v[220:223], v[4:7]
	v_mfma_f32_16x16x32_bf16 v[0:3], v[174:177], v[220:223], v[0:3]
	v_mfma_f32_16x16x32_bf16 v[44:47], v[170:173], v[186:189], v[44:47]
	v_mfma_f32_16x16x32_bf16 v[40:43], v[178:181], v[186:189], v[40:43]
	v_mfma_f32_16x16x32_bf16 v[28:31], v[170:173], v[198:201], v[28:31]
	v_mfma_f32_16x16x32_bf16 v[24:27], v[178:181], v[198:201], v[24:27]
	v_mfma_f32_16x16x32_bf16 v[12:15], v[170:173], v[216:219], v[12:15]
	v_mfma_f32_16x16x32_bf16 v[8:11], v[178:181], v[216:219], v[8:11]
	v_mfma_f32_16x16x32_bf16 v[4:7], v[170:173], v[224:227], v[4:7]
	v_mfma_f32_16x16x32_bf16 v[0:3], v[178:181], v[224:227], v[0:3]
	s_barrier
	s_setprio 0
	s_add_i32 s45, 0, 0x18000
	s_add_i32 s46, 0, 0x1c000
	v_add_u32_e32 v162, s45, v145
	v_add_u32_e32 v178, s46, v145
	ds_read_b128 v[150:153], v162
	ds_read_b128 v[154:157], v162 offset:1024
	ds_read_b128 v[158:161], v162 offset:2048
	ds_read_b128 v[162:165], v162 offset:3072
	ds_read_b128 v[166:169], v178
	ds_read_b128 v[170:173], v178 offset:1024
	ds_read_b128 v[174:177], v178 offset:2048
	ds_read_b128 v[178:181], v178 offset:3072
	s_add_u32 s22, s22, 0x100000
	s_addc_u32 s23, s23, 0
	s_mov_b32 m0, s28
	v_lshl_add_u64 v[232:233], s[22:23], 0, v[134:135]
	ds_read_b128 v[182:185], v149 offset:32768
	ds_read_b128 v[186:189], v149 offset:33792
	ds_read_b128 v[190:193], v149 offset:34816
	ds_read_b128 v[198:201], v149 offset:35840
	ds_read_b128 v[202:205], v149 offset:36864
	ds_read_b128 v[216:219], v149 offset:37888
	ds_read_b128 v[220:223], v149 offset:38912
	ds_read_b128 v[224:227], v149 offset:39936
	global_load_lds_dwordx4 v[232:233], off
	v_lshl_add_u64 v[232:233], s[22:23], 0, v[130:131]
	s_mov_b32 m0, s29
	s_nop 0
	global_load_lds_dwordx4 v[232:233], off
	s_waitcnt vmcnt(8)
	s_waitcnt lgkmcnt(0)
	s_setprio 1
	s_barrier
	v_mfma_f32_16x16x32_bf16 v[124:127], v[150:153], v[182:185], v[124:127]
	v_mfma_f32_16x16x32_bf16 v[120:123], v[158:161], v[182:185], v[120:123]
	v_mfma_f32_16x16x32_bf16 v[116:119], v[150:153], v[190:193], v[116:119]
	v_mfma_f32_16x16x32_bf16 v[112:115], v[158:161], v[190:193], v[112:115]
	v_mfma_f32_16x16x32_bf16 v[100:103], v[150:153], v[202:205], v[100:103]
	v_mfma_f32_16x16x32_bf16 v[96:99], v[158:161], v[202:205], v[96:99]
	v_mfma_f32_16x16x32_bf16 v[84:87], v[150:153], v[220:223], v[84:87]
	v_mfma_f32_16x16x32_bf16 v[80:83], v[158:161], v[220:223], v[80:83]
	v_mfma_f32_16x16x32_bf16 v[124:127], v[154:157], v[186:189], v[124:127]
	v_mfma_f32_16x16x32_bf16 v[120:123], v[162:165], v[186:189], v[120:123]
	v_mfma_f32_16x16x32_bf16 v[116:119], v[154:157], v[198:201], v[116:119]
	v_mfma_f32_16x16x32_bf16 v[112:115], v[162:165], v[198:201], v[112:115]
	v_mfma_f32_16x16x32_bf16 v[100:103], v[154:157], v[216:219], v[100:103]
	v_mfma_f32_16x16x32_bf16 v[96:99], v[162:165], v[216:219], v[96:99]
	v_mfma_f32_16x16x32_bf16 v[84:87], v[154:157], v[224:227], v[84:87]
	v_mfma_f32_16x16x32_bf16 v[80:83], v[162:165], v[224:227], v[80:83]
	v_mfma_f32_16x16x32_bf16 v[108:111], v[166:169], v[182:185], v[108:111]
	v_mfma_f32_16x16x32_bf16 v[104:107], v[174:177], v[182:185], v[104:107]
	v_mfma_f32_16x16x32_bf16 v[92:95], v[166:169], v[190:193], v[92:95]
	v_mfma_f32_16x16x32_bf16 v[88:91], v[174:177], v[190:193], v[88:91]
	v_mfma_f32_16x16x32_bf16 v[76:79], v[166:169], v[202:205], v[76:79]
	v_mfma_f32_16x16x32_bf16 v[72:75], v[174:177], v[202:205], v[72:75]
	v_mfma_f32_16x16x32_bf16 v[68:71], v[166:169], v[220:223], v[68:71]
	v_mfma_f32_16x16x32_bf16 v[64:67], v[174:177], v[220:223], v[64:67]
	v_mfma_f32_16x16x32_bf16 v[108:111], v[170:173], v[186:189], v[108:111]
	v_mfma_f32_16x16x32_bf16 v[104:107], v[178:181], v[186:189], v[104:107]
	v_mfma_f32_16x16x32_bf16 v[92:95], v[170:173], v[198:201], v[92:95]
	v_mfma_f32_16x16x32_bf16 v[88:91], v[178:181], v[198:201], v[88:91]
	v_mfma_f32_16x16x32_bf16 v[76:79], v[170:173], v[216:219], v[76:79]
	v_mfma_f32_16x16x32_bf16 v[72:75], v[178:181], v[216:219], v[72:75]
	v_mfma_f32_16x16x32_bf16 v[68:71], v[170:173], v[224:227], v[68:71]
	v_mfma_f32_16x16x32_bf16 v[64:67], v[178:181], v[224:227], v[64:67]
	s_barrier
; #define PG8_STAGE(bufoff, gbase, voff) do { _Pragma("unroll") for (int _i = 0; _i < 2; ++_i) \
;         __builtin_amdgcn_global_load_lds((const unsigned*)((const char*)(gbase) + (voff)[_i]), (LAS unsigned*)(lds + (bufoff) + ldsw + _i * 8192), 16, 0, 0); } while (0)
; #define PG8_LDA(dst, b, h) do { _Pragma("unroll") for (int m = 0; m < 4; ++m) _Pragma("unroll") for (int k = 0; k < 2; ++k) dst[m][k] = *(const LAS bf16x8*)(lds + PG8_SA(b, h) + aoff + m * 2048 + k * 1024); } while (0)
; #define PG8_MMA(ai, bj, At, Bt) do { __builtin_amdgcn_s_setprio(1); _Pragma("unroll") for (int m = 0; m < 4; ++m) _Pragma("unroll") for (int n = 0; n < 2; ++n) _Pragma("unroll") for (int k = 0; k < 2; ++k) \
;         acc[ai][bj][m][n] = __builtin_amdgcn_mfma_f32_16x16x32_bf16(Bt[n][k], At[m][k], acc[ai][bj][m][n], 0, 0, 0); __builtin_amdgcn_s_setprio(0); } while (0)
; #define PG8_WAIT_V(n) asm volatile("s_waitcnt vmcnt(" #n ")" ::: "memory")
; #define PG8_WAIT_L(n) asm volatile("s_waitcnt lgkmcnt(" #n ")" ::: "memory")
; #define PG8_BAR __builtin_amdgcn_s_barrier()
; #define PG8_SCHED __builtin_amdgcn_sched_barrier(0)
; template <class Epi, bool ALIGN_EPI, bool SP2 = PG8_SP2_DEFAULT>
; __device__ __forceinline__ void gemm_phase(LAS unsigned char* lds, const Gemm g, const StaticOrder& S, const Epi& E) {
;     ...
;         for (int t = 0; t < nt; t += 2) {
;     ...
;             PG8_LDA(At, 1, 1); PG8_STAGE(PG8_SB(1, 0), b3, voffB); PG8_STAGE(PG8_SB(1, 1), b3 + hstepB, voffB); PG8_STAGE(PG8_SA(1, 0), a3, voffA);
;             PG8_WAIT_V(8); PG8_WAIT_L(0); PG8_BAR; PG8_MMA(1, 0, At, B0); PG8_MMA(1, 1, At, B1); PG8_BAR; PG8_SCHED;
;     ...
;         if constexpr (ALIGN_EPI) { if (wr == 0) PG8_BAR; }
	s_setprio 0
	s_add_i32 s22, s45, s24
	v_lshl_add_u64 v[206:207], v[206:207], 0, s[4:5]
	s_mov_b32 m0, s22
	ds_read_b128 v[182:185], v149 offset:49152
	ds_read_b128 v[186:189], v149 offset:50176
	ds_read_b128 v[190:193], v149 offset:51200
	ds_read_b128 v[198:201], v149 offset:52224
	ds_read_b128 v[202:205], v149 offset:53248
	ds_read_b128 v[216:219], v149 offset:54272
	ds_read_b128 v[220:223], v149 offset:55296
	ds_read_b128 v[224:227], v149 offset:56320
	global_load_lds_dwordx4 v[206:207], off
	s_add_i32 m0, s22, 0x2000
	s_add_u32 s20, s20, 0x100080
	v_lshl_add_u64 v[206:207], v[210:211], 0, s[4:5]
	s_addc_u32 s21, s21, 0
	s_add_i32 s22, s46, s24
	global_load_lds_dwordx4 v[206:207], off
	v_lshl_add_u64 v[206:207], s[20:21], 0, v[132:133]
	s_mov_b32 m0, s22
	s_nop 0
	global_load_lds_dwordx4 v[206:207], off
	v_lshl_add_u64 v[206:207], s[20:21], 0, v[128:129]
	s_add_i32 m0, s22, 0x2000
	s_nop 0
	global_load_lds_dwordx4 v[206:207], off
	v_lshl_add_u64 v[206:207], v[228:229], 0, s[4:5]
	s_mov_b32 m0, s33
	s_nop 0
	global_load_lds_dwordx4 v[206:207], off
	v_lshl_add_u64 v[206:207], v[230:231], 0, s[4:5]
	s_mov_b32 m0, s34
	s_nop 0
	global_load_lds_dwordx4 v[206:207], off
	s_nop 0
	s_waitcnt vmcnt(8)
	s_waitcnt lgkmcnt(0)
	s_setprio 1
	s_barrier
	v_mfma_f32_16x16x32_bf16 v[60:63], v[150:153], v[182:185], v[60:63]
	v_mfma_f32_16x16x32_bf16 v[56:59], v[158:161], v[182:185], v[56:59]
	v_mfma_f32_16x16x32_bf16 v[52:55], v[150:153], v[190:193], v[52:55]
	v_mfma_f32_16x16x32_bf16 v[48:51], v[158:161], v[190:193], v[48:51]
	v_mfma_f32_16x16x32_bf16 v[36:39], v[150:153], v[202:205], v[36:39]
	v_mfma_f32_16x16x32_bf16 v[32:35], v[158:161], v[202:205], v[32:35]
	v_mfma_f32_16x16x32_bf16 v[20:23], v[150:153], v[220:223], v[20:23]
	v_mfma_f32_16x16x32_bf16 v[16:19], v[158:161], v[220:223], v[16:19]
	v_mfma_f32_16x16x32_bf16 v[60:63], v[154:157], v[186:189], v[60:63]
	v_mfma_f32_16x16x32_bf16 v[56:59], v[162:165], v[186:189], v[56:59]
	v_mfma_f32_16x16x32_bf16 v[52:55], v[154:157], v[198:201], v[52:55]
	v_mfma_f32_16x16x32_bf16 v[48:51], v[162:165], v[198:201], v[48:51]
	v_mfma_f32_16x16x32_bf16 v[36:39], v[154:157], v[216:219], v[36:39]
	v_mfma_f32_16x16x32_bf16 v[32:35], v[162:165], v[216:219], v[32:35]
	v_mfma_f32_16x16x32_bf16 v[20:23], v[154:157], v[224:227], v[20:23]
	v_mfma_f32_16x16x32_bf16 v[16:19], v[162:165], v[224:227], v[16:19]
	v_mfma_f32_16x16x32_bf16 v[44:47], v[166:169], v[182:185], v[44:47]
	v_mfma_f32_16x16x32_bf16 v[40:43], v[174:177], v[182:185], v[40:43]
	v_mfma_f32_16x16x32_bf16 v[28:31], v[166:169], v[190:193], v[28:31]
	v_mfma_f32_16x16x32_bf16 v[24:27], v[174:177], v[190:193], v[24:27]
	v_mfma_f32_16x16x32_bf16 v[12:15], v[166:169], v[202:205], v[12:15]
	v_mfma_f32_16x16x32_bf16 v[8:11], v[174:177], v[202:205], v[8:11]
	v_mfma_f32_16x16x32_bf16 v[4:7], v[166:169], v[220:223], v[4:7]
	v_mfma_f32_16x16x32_bf16 v[0:3], v[174:177], v[220:223], v[0:3]
	v_mfma_f32_16x16x32_bf16 v[44:47], v[170:173], v[186:189], v[44:47]
	v_mfma_f32_16x16x32_bf16 v[40:43], v[178:181], v[186:189], v[40:43]
	v_mfma_f32_16x16x32_bf16 v[28:31], v[170:173], v[198:201], v[28:31]
	v_mfma_f32_16x16x32_bf16 v[24:27], v[178:181], v[198:201], v[24:27]
	v_mfma_f32_16x16x32_bf16 v[12:15], v[170:173], v[216:219], v[12:15]
	v_mfma_f32_16x16x32_bf16 v[8:11], v[178:181], v[216:219], v[8:11]
	v_mfma_f32_16x16x32_bf16 v[4:7], v[170:173], v[224:227], v[4:7]
	v_mfma_f32_16x16x32_bf16 v[0:3], v[178:181], v[224:227], v[0:3]
	s_barrier
	s_setprio 0
	s_add_i32 s44, s44, 2
	s_add_u32 s18, s18, 0x100
	s_addc_u32 s19, s19, 0
	s_add_u32 s42, s42, 0x100
	s_addc_u32 s43, s43, 0
	s_cmp_gt_u32 s44, 61
	s_cbranch_scc0 .LBB0_250
	s_and_b64 vcc, exec, s[6:7]
	s_cbranch_vccz .LBB0_253
	s_barrier

; #define PG8_STAGE(bufoff, gbase, voff) do { _Pragma("unroll") for (int _i = 0; _i < 2; ++_i) \
;         __builtin_amdgcn_global_load_lds((const unsigned*)((const char*)(gbase) + (voff)[_i]), (LAS unsigned*)(lds + (bufoff) + ldsw + _i * 8192), 16, 0, 0); } while (0)
; #define PG8_LDA(dst, b, h) do { _Pragma("unroll") for (int m = 0; m < 4; ++m) _Pragma("unroll") for (int k = 0; k < 2; ++k) dst[m][k] = *(const LAS bf16x8*)(lds + PG8_SA(b, h) + aoff + m * 2048 + k * 1024); } while (0)
; #define PG8_LDB(dst, b, h) do { _Pragma("unroll") for (int n = 0; n < 2; ++n) _Pragma("unroll") for (int k = 0; k < 2; ++k) dst[n][k] = *(const LAS bf16x8*)(lds + PG8_SB(b, h) + boff + n * 2048 + k * 1024); } while (0)
; #define PG8_MMA(ai, bj, At, Bt) do { __builtin_amdgcn_s_setprio(1); _Pragma("unroll") for (int m = 0; m < 4; ++m) _Pragma("unroll") for (int n = 0; n < 2; ++n) _Pragma("unroll") for (int k = 0; k < 2; ++k) \
;         acc[ai][bj][m][n] = __builtin_amdgcn_mfma_f32_16x16x32_bf16(Bt[n][k], At[m][k], acc[ai][bj][m][n], 0, 0, 0); __builtin_amdgcn_s_setprio(0); } while (0)
; #define PG8_WAIT_V(n) asm volatile("s_waitcnt vmcnt(" #n ")" ::: "memory")
; #define PG8_WAIT_L(n) asm volatile("s_waitcnt lgkmcnt(" #n ")" ::: "memory")
; #define PG8_BAR __builtin_amdgcn_s_barrier()
; #define PG8_SCHED __builtin_amdgcn_sched_barrier(0)
; template <class Epi, bool ALIGN_EPI, bool SP2 = PG8_SP2_DEFAULT>
; __device__ __forceinline__ void gemm_phase(LAS unsigned char* lds, const Gemm g, const StaticOrder& S, const Epi& E) {
;     ...
;             const bool last = (t == nt - 2);
;             const char* a1 = cA + (size_t)(t + 1) * kstep;
;             const char* a2 = last ? nA : cA + (size_t)(t + 2) * kstep; const char* b2 = last ? nB : cB + (size_t)(t + 2) * kstep;
;             const char* a3 = a2 + kstep; const char* b3 = b2 + kstep;
;             if constexpr (SP2) {
;             PG8_LDB(B0, 0, 0); PG8_LDB(B1, 0, 1); PG8_SCHED; PG8_LDA(At, 0, 0); PG8_STAGE(PG8_SA(1, 1), a1 + hstepA, voffA);
;             PG8_WAIT_V(8); PG8_WAIT_L(0); PG8_BAR; PG8_MMA(0, 0, At, B0); PG8_MMA(0, 1, At, B1); PG8_BAR; PG8_SCHED;
;             PG8_LDA(At, 0, 1); PG8_STAGE(PG8_SB(0, 0), b2, voffB); PG8_STAGE(PG8_SB(0, 1), b2 + hstepB, voffB); PG8_STAGE(PG8_SA(0, 0), a2, voffA);
.LBB0_428:
	ds_read_b128 v[128:131], v165
	ds_read_b128 v[132:135], v165 offset:1024
	ds_read_b128 v[136:139], v165 offset:2048
	ds_read_b128 v[140:143], v165 offset:3072
	ds_read_b128 v[168:171], v166
	ds_read_b128 v[172:175], v166 offset:1024
	ds_read_b128 v[176:179], v166 offset:2048
	ds_read_b128 v[180:183], v166 offset:3072
	s_add_u32 s24, s22, 0xfffe0080
	s_addc_u32 s25, s23, -1
	s_cmp_eq_u32 s51, 4
	s_cselect_b32 s27, s15, s25
	s_cselect_b32 s26, s47, s24
	s_cselect_b32 s25, s13, s50
	s_cselect_b32 s24, s48, s49
	v_lshl_add_u64 v[160:161], s[22:23], 0, v[152:153]
	s_add_i32 m0, s21, 0xc000
	ds_read_b128 v[184:187], v167
	ds_read_b128 v[188:191], v167 offset:1024
	ds_read_b128 v[198:201], v167 offset:2048
	ds_read_b128 v[202:205], v167 offset:3072
	ds_read_b128 v[216:219], v167 offset:4096
	ds_read_b128 v[220:223], v167 offset:5120
	ds_read_b128 v[224:227], v167 offset:6144
	ds_read_b128 v[228:231], v167 offset:7168
	global_load_lds_dwordx4 v[160:161], off
	v_lshl_add_u64 v[160:161], s[22:23], 0, v[154:155]
	s_add_i32 m0, s21, 0xe000
	s_nop 0
	global_load_lds_dwordx4 v[160:161], off
	s_waitcnt vmcnt(8)
	s_waitcnt lgkmcnt(0)
	s_setprio 1
	s_barrier
	v_mfma_f32_16x16x32_bf16 v[124:127], v[128:131], v[184:187], v[124:127]
	v_mfma_f32_16x16x32_bf16 v[120:123], v[136:139], v[184:187], v[120:123]
	v_mfma_f32_16x16x32_bf16 v[116:119], v[128:131], v[198:201], v[116:119]
	v_mfma_f32_16x16x32_bf16 v[112:115], v[136:139], v[198:201], v[112:115]
	v_mfma_f32_16x16x32_bf16 v[108:111], v[128:131], v[216:219], v[108:111]
	v_mfma_f32_16x16x32_bf16 v[100:103], v[136:139], v[216:219], v[100:103]
	v_mfma_f32_16x16x32_bf16 v[80:83], v[128:131], v[224:227], v[80:83]
	v_mfma_f32_16x16x32_bf16 v[72:75], v[136:139], v[224:227], v[72:75]
	v_mfma_f32_16x16x32_bf16 v[124:127], v[132:135], v[188:191], v[124:127]
	v_mfma_f32_16x16x32_bf16 v[120:123], v[140:143], v[188:191], v[120:123]
	v_mfma_f32_16x16x32_bf16 v[116:119], v[132:135], v[202:205], v[116:119]
	v_mfma_f32_16x16x32_bf16 v[112:115], v[140:143], v[202:205], v[112:115]
	v_mfma_f32_16x16x32_bf16 v[108:111], v[132:135], v[220:223], v[108:111]
	v_mfma_f32_16x16x32_bf16 v[100:103], v[140:143], v[220:223], v[100:103]
	v_mfma_f32_16x16x32_bf16 v[80:83], v[132:135], v[228:231], v[80:83]
	v_mfma_f32_16x16x32_bf16 v[72:75], v[140:143], v[228:231], v[72:75]
	v_mfma_f32_16x16x32_bf16 v[104:107], v[168:171], v[184:187], v[104:107]
	v_mfma_f32_16x16x32_bf16 v[96:99], v[176:179], v[184:187], v[96:99]
	v_mfma_f32_16x16x32_bf16 v[92:95], v[168:171], v[198:201], v[92:95]
	v_mfma_f32_16x16x32_bf16 v[88:91], v[176:179], v[198:201], v[88:91]
	v_mfma_f32_16x16x32_bf16 v[84:87], v[168:171], v[216:219], v[84:87]
	v_mfma_f32_16x16x32_bf16 v[76:79], v[176:179], v[216:219], v[76:79]
	v_mfma_f32_16x16x32_bf16 v[68:71], v[168:171], v[224:227], v[68:71]
	v_mfma_f32_16x16x32_bf16 v[64:67], v[176:179], v[224:227], v[64:67]
	v_mfma_f32_16x16x32_bf16 v[104:107], v[172:175], v[188:191], v[104:107]
	v_mfma_f32_16x16x32_bf16 v[96:99], v[180:183], v[188:191], v[96:99]
	v_mfma_f32_16x16x32_bf16 v[92:95], v[172:175], v[202:205], v[92:95]
	v_mfma_f32_16x16x32_bf16 v[88:91], v[180:183], v[202:205], v[88:91]
	v_mfma_f32_16x16x32_bf16 v[84:87], v[172:175], v[220:223], v[84:87]
	v_mfma_f32_16x16x32_bf16 v[76:79], v[180:183], v[220:223], v[76:79]
	v_mfma_f32_16x16x32_bf16 v[68:71], v[172:175], v[228:231], v[68:71]
	v_mfma_f32_16x16x32_bf16 v[64:67], v[180:183], v[228:231], v[64:67]
	s_barrier
	s_setprio 0
	s_add_i32 s52, s40, s29
	v_lshl_add_u64 v[160:161], s[24:25], 0, v[146:147]
	s_mov_b32 m0, s52
	ds_read_b128 v[184:187], v167 offset:16384
	ds_read_b128 v[188:191], v167 offset:17408
	ds_read_b128 v[198:201], v167 offset:18432
	ds_read_b128 v[202:205], v167 offset:19456
	ds_read_b128 v[216:219], v167 offset:20480
	ds_read_b128 v[220:223], v167 offset:21504
	ds_read_b128 v[224:227], v167 offset:22528
	ds_read_b128 v[228:231], v167 offset:23552
	global_load_lds_dwordx4 v[160:161], off
	s_add_i32 m0, s52, 0x2000
	s_add_u32 s52, s24, 0x20000
	v_lshl_add_u64 v[192:193], s[24:25], 0, v[150:151]
	s_addc_u32 s53, s25, 0
	s_add_i32 s54, s41, s29
	global_load_lds_dwordx4 v[192:193], off
	v_lshl_add_u64 v[206:207], s[52:53], 0, v[146:147]
	s_mov_b32 m0, s54
	v_lshl_add_u64 v[210:211], s[26:27], 0, v[148:149]
	global_load_lds_dwordx4 v[206:207], off
	v_lshl_add_u64 v[206:207], s[52:53], 0, v[150:151]
	s_add_i32 m0, s54, 0x2000
	s_nop 0
	global_load_lds_dwordx4 v[206:207], off
	v_lshl_add_u64 v[206:207], s[26:27], 0, v[144:145]
	s_mov_b32 m0, s21
	s_nop 0
	global_load_lds_dwordx4 v[206:207], off
	s_mov_b32 m0, s30
	s_nop 0
	global_load_lds_dwordx4 v[210:211], off
	s_waitcnt vmcnt(8)
	s_waitcnt lgkmcnt(0)
	s_setprio 1
	s_barrier
; #define PG8_STAGE(bufoff, gbase, voff) do { _Pragma("unroll") for (int _i = 0; _i < 2; ++_i) \
;         __builtin_amdgcn_global_load_lds((const unsigned*)((const char*)(gbase) + (voff)[_i]), (LAS unsigned*)(lds + (bufoff) + ldsw + _i * 8192), 16, 0, 0); } while (0)
; #define PG8_LDA(dst, b, h) do { _Pragma("unroll") for (int m = 0; m < 4; ++m) _Pragma("unroll") for (int k = 0; k < 2; ++k) dst[m][k] = *(const LAS bf16x8*)(lds + PG8_SA(b, h) + aoff + m * 2048 + k * 1024); } while (0)
; #define PG8_LDB(dst, b, h) do { _Pragma("unroll") for (int n = 0; n < 2; ++n) _Pragma("unroll") for (int k = 0; k < 2; ++k) dst[n][k] = *(const LAS bf16x8*)(lds + PG8_SB(b, h) + boff + n * 2048 + k * 1024); } while (0)
; #define PG8_MMA(ai, bj, At, Bt) do { __builtin_amdgcn_s_setprio(1); _Pragma("unroll") for (int m = 0; m < 4; ++m) _Pragma("unroll") for (int n = 0; n < 2; ++n) _Pragma("unroll") for (int k = 0; k < 2; ++k) \
;         acc[ai][bj][m][n] = __builtin_amdgcn_mfma_f32_16x16x32_bf16(Bt[n][k], At[m][k], acc[ai][bj][m][n], 0, 0, 0); __builtin_amdgcn_s_setprio(0); } while (0)
; #define PG8_WAIT_V(n) asm volatile("s_waitcnt vmcnt(" #n ")" ::: "memory")
; #define PG8_WAIT_L(n) asm volatile("s_waitcnt lgkmcnt(" #n ")" ::: "memory")
; #define PG8_BAR __builtin_amdgcn_s_barrier()
; #define PG8_SCHED __builtin_amdgcn_sched_barrier(0)
; template <class Epi, bool ALIGN_EPI, bool SP2 = PG8_SP2_DEFAULT>
; __device__ __forceinline__ void gemm_phase(LAS unsigned char* lds, const Gemm g, const StaticOrder& S, const Epi& E) {
;     ...
;             PG8_WAIT_V(8); PG8_WAIT_L(0); PG8_BAR; PG8_MMA(1, 0, At, B0); PG8_MMA(1, 1, At, B1); PG8_BAR; PG8_SCHED;
;             PG8_LDB(B0, 1, 0); PG8_LDB(B1, 1, 1); PG8_SCHED; PG8_LDA(At, 1, 0); PG8_STAGE(PG8_SA(0, 1), a2 + hstepA, voffA);
;             PG8_WAIT_V(8); PG8_WAIT_L(0); PG8_BAR; PG8_MMA(0, 0, At, B0); PG8_MMA(0, 1, At, B1); PG8_BAR; PG8_SCHED;
	v_mfma_f32_16x16x32_bf16 v[60:63], v[128:131], v[184:187], v[60:63]
	v_mfma_f32_16x16x32_bf16 v[56:59], v[136:139], v[184:187], v[56:59]
	v_mfma_f32_16x16x32_bf16 v[52:55], v[128:131], v[198:201], v[52:55]
	v_mfma_f32_16x16x32_bf16 v[44:47], v[136:139], v[198:201], v[44:47]
	v_mfma_f32_16x16x32_bf16 v[36:39], v[128:131], v[216:219], v[36:39]
	v_mfma_f32_16x16x32_bf16 v[28:31], v[136:139], v[216:219], v[28:31]
	v_mfma_f32_16x16x32_bf16 v[20:23], v[128:131], v[224:227], v[20:23]
	v_mfma_f32_16x16x32_bf16 v[12:15], v[136:139], v[224:227], v[12:15]
	v_mfma_f32_16x16x32_bf16 v[60:63], v[132:135], v[188:191], v[60:63]
	v_mfma_f32_16x16x32_bf16 v[56:59], v[140:143], v[188:191], v[56:59]
	v_mfma_f32_16x16x32_bf16 v[52:55], v[132:135], v[202:205], v[52:55]
	v_mfma_f32_16x16x32_bf16 v[44:47], v[140:143], v[202:205], v[44:47]
	v_mfma_f32_16x16x32_bf16 v[36:39], v[132:135], v[220:223], v[36:39]
	v_mfma_f32_16x16x32_bf16 v[28:31], v[140:143], v[220:223], v[28:31]
	v_mfma_f32_16x16x32_bf16 v[20:23], v[132:135], v[228:231], v[20:23]
	v_mfma_f32_16x16x32_bf16 v[12:15], v[140:143], v[228:231], v[12:15]
	v_mfma_f32_16x16x32_bf16 v[48:51], v[168:171], v[184:187], v[48:51]
	v_mfma_f32_16x16x32_bf16 v[40:43], v[176:179], v[184:187], v[40:43]
	v_mfma_f32_16x16x32_bf16 v[32:35], v[168:171], v[198:201], v[32:35]
	v_mfma_f32_16x16x32_bf16 v[24:27], v[176:179], v[198:201], v[24:27]
	v_mfma_f32_16x16x32_bf16 v[16:19], v[168:171], v[216:219], v[16:19]
	v_mfma_f32_16x16x32_bf16 v[8:11], v[176:179], v[216:219], v[8:11]
	v_mfma_f32_16x16x32_bf16 v[4:7], v[168:171], v[224:227], v[4:7]
	v_mfma_f32_16x16x32_bf16 v[0:3], v[176:179], v[224:227], v[0:3]
	v_mfma_f32_16x16x32_bf16 v[48:51], v[172:175], v[188:191], v[48:51]
	v_mfma_f32_16x16x32_bf16 v[40:43], v[180:183], v[188:191], v[40:43]
	v_mfma_f32_16x16x32_bf16 v[32:35], v[172:175], v[202:205], v[32:35]
	v_mfma_f32_16x16x32_bf16 v[24:27], v[180:183], v[202:205], v[24:27]
	v_mfma_f32_16x16x32_bf16 v[16:19], v[172:175], v[220:223], v[16:19]
	v_mfma_f32_16x16x32_bf16 v[8:11], v[180:183], v[220:223], v[8:11]
	v_mfma_f32_16x16x32_bf16 v[4:7], v[172:175], v[228:231], v[4:7]
	v_mfma_f32_16x16x32_bf16 v[0:3], v[180:183], v[228:231], v[0:3]
	s_barrier
	s_setprio 0
	s_add_i32 s52, 0, 0x18000
	s_add_i32 s53, 0, 0x1c000
	v_add_u32_e32 v140, s52, v163
	v_add_u32_e32 v180, s53, v163
	ds_read_b128 v[128:131], v140
	ds_read_b128 v[132:135], v140 offset:1024
	ds_read_b128 v[136:139], v140 offset:2048
	ds_read_b128 v[140:143], v140 offset:3072
	ds_read_b128 v[168:171], v180
	ds_read_b128 v[172:175], v180 offset:1024
	ds_read_b128 v[176:179], v180 offset:2048
	ds_read_b128 v[180:183], v180 offset:3072
	s_add_u32 s26, s26, 0x20000
	s_addc_u32 s27, s27, 0
	s_mov_b32 m0, s31
	v_lshl_add_u64 v[232:233], s[26:27], 0, v[144:145]
	ds_read_b128 v[184:187], v167 offset:32768
	ds_read_b128 v[188:191], v167 offset:33792
	ds_read_b128 v[198:201], v167 offset:34816
	ds_read_b128 v[202:205], v167 offset:35840
	ds_read_b128 v[216:219], v167 offset:36864
	ds_read_b128 v[220:223], v167 offset:37888
	ds_read_b128 v[224:227], v167 offset:38912
	ds_read_b128 v[228:231], v167 offset:39936
	global_load_lds_dwordx4 v[232:233], off
	v_lshl_add_u64 v[232:233], s[26:27], 0, v[148:149]
	s_mov_b32 m0, s34
	s_nop 0
	global_load_lds_dwordx4 v[232:233], off
	s_waitcnt vmcnt(8)
	s_waitcnt lgkmcnt(0)
	s_setprio 1
	s_barrier
	v_mfma_f32_16x16x32_bf16 v[124:127], v[128:131], v[184:187], v[124:127]
	v_mfma_f32_16x16x32_bf16 v[120:123], v[136:139], v[184:187], v[120:123]
	v_mfma_f32_16x16x32_bf16 v[116:119], v[128:131], v[198:201], v[116:119]
	v_mfma_f32_16x16x32_bf16 v[112:115], v[136:139], v[198:201], v[112:115]
	v_mfma_f32_16x16x32_bf16 v[108:111], v[128:131], v[216:219], v[108:111]
	v_mfma_f32_16x16x32_bf16 v[100:103], v[136:139], v[216:219], v[100:103]
	v_mfma_f32_16x16x32_bf16 v[80:83], v[128:131], v[224:227], v[80:83]
	v_mfma_f32_16x16x32_bf16 v[72:75], v[136:139], v[224:227], v[72:75]
	v_mfma_f32_16x16x32_bf16 v[124:127], v[132:135], v[188:191], v[124:127]
	v_mfma_f32_16x16x32_bf16 v[120:123], v[140:143], v[188:191], v[120:123]
	v_mfma_f32_16x16x32_bf16 v[116:119], v[132:135], v[202:205], v[116:119]
	v_mfma_f32_16x16x32_bf16 v[112:115], v[140:143], v[202:205], v[112:115]
	v_mfma_f32_16x16x32_bf16 v[108:111], v[132:135], v[220:223], v[108:111]
	v_mfma_f32_16x16x32_bf16 v[100:103], v[140:143], v[220:223], v[100:103]
	v_mfma_f32_16x16x32_bf16 v[80:83], v[132:135], v[228:231], v[80:83]
	v_mfma_f32_16x16x32_bf16 v[72:75], v[140:143], v[228:231], v[72:75]
	v_mfma_f32_16x16x32_bf16 v[104:107], v[168:171], v[184:187], v[104:107]
	v_mfma_f32_16x16x32_bf16 v[96:99], v[176:179], v[184:187], v[96:99]
	v_mfma_f32_16x16x32_bf16 v[92:95], v[168:171], v[198:201], v[92:95]
	v_mfma_f32_16x16x32_bf16 v[88:91], v[176:179], v[198:201], v[88:91]
	v_mfma_f32_16x16x32_bf16 v[84:87], v[168:171], v[216:219], v[84:87]
	v_mfma_f32_16x16x32_bf16 v[76:79], v[176:179], v[216:219], v[76:79]
	v_mfma_f32_16x16x32_bf16 v[68:71], v[168:171], v[224:227], v[68:71]
	v_mfma_f32_16x16x32_bf16 v[64:67], v[176:179], v[224:227], v[64:67]
	v_mfma_f32_16x16x32_bf16 v[104:107], v[172:175], v[188:191], v[104:107]
	v_mfma_f32_16x16x32_bf16 v[96:99], v[180:183], v[188:191], v[96:99]
	v_mfma_f32_16x16x32_bf16 v[92:95], v[172:175], v[202:205], v[92:95]
	v_mfma_f32_16x16x32_bf16 v[88:91], v[180:183], v[202:205], v[88:91]
	v_mfma_f32_16x16x32_bf16 v[84:87], v[172:175], v[220:223], v[84:87]
	v_mfma_f32_16x16x32_bf16 v[76:79], v[180:183], v[220:223], v[76:79]
	v_mfma_f32_16x16x32_bf16 v[68:71], v[172:175], v[228:231], v[68:71]
	v_mfma_f32_16x16x32_bf16 v[64:67], v[180:183], v[228:231], v[64:67]
	s_barrier
; #define PG8_STAGE(bufoff, gbase, voff) do { _Pragma("unroll") for (int _i = 0; _i < 2; ++_i) \
;         __builtin_amdgcn_global_load_lds((const unsigned*)((const char*)(gbase) + (voff)[_i]), (LAS unsigned*)(lds + (bufoff) + ldsw + _i * 8192), 16, 0, 0); } while (0)
; #define PG8_LDA(dst, b, h) do { _Pragma("unroll") for (int m = 0; m < 4; ++m) _Pragma("unroll") for (int k = 0; k < 2; ++k) dst[m][k] = *(const LAS bf16x8*)(lds + PG8_SA(b, h) + aoff + m * 2048 + k * 1024); } while (0)
; #define PG8_MMA(ai, bj, At, Bt) do { __builtin_amdgcn_s_setprio(1); _Pragma("unroll") for (int m = 0; m < 4; ++m) _Pragma("unroll") for (int n = 0; n < 2; ++n) _Pragma("unroll") for (int k = 0; k < 2; ++k) \
;         acc[ai][bj][m][n] = __builtin_amdgcn_mfma_f32_16x16x32_bf16(Bt[n][k], At[m][k], acc[ai][bj][m][n], 0, 0, 0); __builtin_amdgcn_s_setprio(0); } while (0)
; #define PG8_WAIT_V(n) asm volatile("s_waitcnt vmcnt(" #n ")" ::: "memory")
; #define PG8_WAIT_L(n) asm volatile("s_waitcnt lgkmcnt(" #n ")" ::: "memory")
; #define PG8_BAR __builtin_amdgcn_s_barrier()
; #define PG8_SCHED __builtin_amdgcn_sched_barrier(0)
; template <class Epi, bool ALIGN_EPI, bool SP2 = PG8_SP2_DEFAULT>
; __device__ __forceinline__ void gemm_phase(LAS unsigned char* lds, const Gemm g, const StaticOrder& S, const Epi& E) {
;     ...
;         for (int t = 0; t < nt; t += 2) {
;     ...
;             PG8_LDA(At, 1, 1); PG8_STAGE(PG8_SB(1, 0), b3, voffB); PG8_STAGE(PG8_SB(1, 1), b3 + hstepB, voffB); PG8_STAGE(PG8_SA(1, 0), a3, voffA);
;             PG8_WAIT_V(8); PG8_WAIT_L(0); PG8_BAR; PG8_MMA(1, 0, At, B0); PG8_MMA(1, 1, At, B1); PG8_BAR; PG8_SCHED;
;     ...
;         if constexpr (ALIGN_EPI) { if (wr == 0) PG8_BAR; }
	s_setprio 0
	s_add_i32 s26, s52, s29
	v_lshl_add_u64 v[160:161], v[160:161], 0, s[4:5]
	s_mov_b32 m0, s26
	ds_read_b128 v[184:187], v167 offset:49152
	ds_read_b128 v[188:191], v167 offset:50176
	ds_read_b128 v[198:201], v167 offset:51200
	ds_read_b128 v[202:205], v167 offset:52224
	ds_read_b128 v[216:219], v167 offset:53248
	ds_read_b128 v[220:223], v167 offset:54272
	ds_read_b128 v[224:227], v167 offset:55296
	ds_read_b128 v[228:231], v167 offset:56320
	global_load_lds_dwordx4 v[160:161], off
	s_add_i32 m0, s26, 0x2000
	s_add_u32 s24, s24, 0x20080
	v_lshl_add_u64 v[160:161], v[192:193], 0, s[4:5]
	s_addc_u32 s25, s25, 0
	s_add_i32 s26, s53, s29
	global_load_lds_dwordx4 v[160:161], off
	v_lshl_add_u64 v[160:161], s[24:25], 0, v[146:147]
	s_mov_b32 m0, s26
	s_nop 0
	global_load_lds_dwordx4 v[160:161], off
	v_lshl_add_u64 v[160:161], s[24:25], 0, v[150:151]
	s_add_i32 m0, s26, 0x2000
	s_nop 0
	global_load_lds_dwordx4 v[160:161], off
	v_lshl_add_u64 v[160:161], v[206:207], 0, s[4:5]
	s_mov_b32 m0, s36
	s_nop 0
	global_load_lds_dwordx4 v[160:161], off
	v_lshl_add_u64 v[160:161], v[210:211], 0, s[4:5]
	s_mov_b32 m0, s37
	s_nop 0
	global_load_lds_dwordx4 v[160:161], off
	s_nop 0
	s_waitcnt vmcnt(8)
	s_waitcnt lgkmcnt(0)
	s_setprio 1
	s_barrier
	v_mfma_f32_16x16x32_bf16 v[60:63], v[128:131], v[184:187], v[60:63]
	v_mfma_f32_16x16x32_bf16 v[56:59], v[136:139], v[184:187], v[56:59]
	v_mfma_f32_16x16x32_bf16 v[52:55], v[128:131], v[198:201], v[52:55]
	v_mfma_f32_16x16x32_bf16 v[44:47], v[136:139], v[198:201], v[44:47]
	v_mfma_f32_16x16x32_bf16 v[36:39], v[128:131], v[216:219], v[36:39]
	v_mfma_f32_16x16x32_bf16 v[28:31], v[136:139], v[216:219], v[28:31]
	v_mfma_f32_16x16x32_bf16 v[20:23], v[128:131], v[224:227], v[20:23]
	v_mfma_f32_16x16x32_bf16 v[12:15], v[136:139], v[224:227], v[12:15]
	v_mfma_f32_16x16x32_bf16 v[60:63], v[132:135], v[188:191], v[60:63]
	v_mfma_f32_16x16x32_bf16 v[56:59], v[140:143], v[188:191], v[56:59]
	v_mfma_f32_16x16x32_bf16 v[52:55], v[132:135], v[202:205], v[52:55]
	v_mfma_f32_16x16x32_bf16 v[44:47], v[140:143], v[202:205], v[44:47]
	v_mfma_f32_16x16x32_bf16 v[36:39], v[132:135], v[220:223], v[36:39]
	v_mfma_f32_16x16x32_bf16 v[28:31], v[140:143], v[220:223], v[28:31]
	v_mfma_f32_16x16x32_bf16 v[20:23], v[132:135], v[228:231], v[20:23]
	v_mfma_f32_16x16x32_bf16 v[12:15], v[140:143], v[228:231], v[12:15]
	v_mfma_f32_16x16x32_bf16 v[48:51], v[168:171], v[184:187], v[48:51]
	v_mfma_f32_16x16x32_bf16 v[40:43], v[176:179], v[184:187], v[40:43]
	v_mfma_f32_16x16x32_bf16 v[32:35], v[168:171], v[198:201], v[32:35]
	v_mfma_f32_16x16x32_bf16 v[24:27], v[176:179], v[198:201], v[24:27]
	v_mfma_f32_16x16x32_bf16 v[16:19], v[168:171], v[216:219], v[16:19]
	v_mfma_f32_16x16x32_bf16 v[8:11], v[176:179], v[216:219], v[8:11]
	v_mfma_f32_16x16x32_bf16 v[4:7], v[168:171], v[224:227], v[4:7]
	v_mfma_f32_16x16x32_bf16 v[0:3], v[176:179], v[224:227], v[0:3]
	v_mfma_f32_16x16x32_bf16 v[48:51], v[172:175], v[188:191], v[48:51]
	v_mfma_f32_16x16x32_bf16 v[40:43], v[180:183], v[188:191], v[40:43]
	v_mfma_f32_16x16x32_bf16 v[32:35], v[172:175], v[202:205], v[32:35]
	v_mfma_f32_16x16x32_bf16 v[24:27], v[180:183], v[202:205], v[24:27]
	v_mfma_f32_16x16x32_bf16 v[16:19], v[172:175], v[220:223], v[16:19]
	v_mfma_f32_16x16x32_bf16 v[8:11], v[180:183], v[220:223], v[8:11]
	v_mfma_f32_16x16x32_bf16 v[4:7], v[172:175], v[228:231], v[4:7]
	v_mfma_f32_16x16x32_bf16 v[0:3], v[180:183], v[228:231], v[0:3]
	s_barrier
	s_setprio 0
	s_add_i32 s51, s51, 2
	s_add_u32 s22, s22, 0x100
	s_addc_u32 s23, s23, 0
	s_add_u32 s49, s49, 0x100
	s_addc_u32 s50, s50, 0
	s_cmp_gt_u32 s51, 5
	s_cbranch_scc0 .LBB0_428
	s_and_b64 vcc, exec, s[6:7]
	s_cbranch_vccz .LBB0_431
	s_barrier

; #define PG8_STAGE(bufoff, gbase, voff) do { _Pragma("unroll") for (int _i = 0; _i < 2; ++_i) \
;         __builtin_amdgcn_global_load_lds((const unsigned*)((const char*)(gbase) + (voff)[_i]), (LAS unsigned*)(lds + (bufoff) + ldsw + _i * 8192), 16, 0, 0); } while (0)
; #define PG8_LDA(dst, b, h) do { _Pragma("unroll") for (int m = 0; m < 4; ++m) _Pragma("unroll") for (int k = 0; k < 2; ++k) dst[m][k] = *(const LAS bf16x8*)(lds + PG8_SA(b, h) + aoff + m * 2048 + k * 1024); } while (0)
; #define PG8_LDB(dst, b, h) do { _Pragma("unroll") for (int n = 0; n < 2; ++n) _Pragma("unroll") for (int k = 0; k < 2; ++k) dst[n][k] = *(const LAS bf16x8*)(lds + PG8_SB(b, h) + boff + n * 2048 + k * 1024); } while (0)
; #define PG8_MMA(ai, bj, At, Bt) do { __builtin_amdgcn_s_setprio(1); _Pragma("unroll") for (int m = 0; m < 4; ++m) _Pragma("unroll") for (int n = 0; n < 2; ++n) _Pragma("unroll") for (int k = 0; k < 2; ++k) \
;         acc[ai][bj][m][n] = __builtin_amdgcn_mfma_f32_16x16x32_bf16(Bt[n][k], At[m][k], acc[ai][bj][m][n], 0, 0, 0); __builtin_amdgcn_s_setprio(0); } while (0)
; #define PG8_WAIT_V(n) asm volatile("s_waitcnt vmcnt(" #n ")" ::: "memory")
; #define PG8_WAIT_L(n) asm volatile("s_waitcnt lgkmcnt(" #n ")" ::: "memory")
; #define PG8_BAR __builtin_amdgcn_s_barrier()
; #define PG8_SCHED __builtin_amdgcn_sched_barrier(0)
; template <class Epi, bool ALIGN_EPI, bool SP2 = PG8_SP2_DEFAULT>
; __device__ __forceinline__ void gemm_phase(LAS unsigned char* lds, const Gemm g, const StaticOrder& S, const Epi& E) {
;     ...
;             const bool last = (t == nt - 2);
;             const char* a1 = cA + (size_t)(t + 1) * kstep;
;             const char* a2 = last ? nA : cA + (size_t)(t + 2) * kstep; const char* b2 = last ? nB : cB + (size_t)(t + 2) * kstep;
;             const char* a3 = a2 + kstep; const char* b3 = b2 + kstep;
;             if constexpr (SP2) {
;             PG8_LDB(B0, 0, 0); PG8_LDB(B1, 0, 1); PG8_SCHED; PG8_LDA(At, 0, 0); PG8_STAGE(PG8_SA(1, 1), a1 + hstepA, voffA);
;             PG8_WAIT_V(8); PG8_WAIT_L(0); PG8_BAR; PG8_MMA(0, 0, At, B0); PG8_MMA(0, 1, At, B1); PG8_BAR; PG8_SCHED;
;             PG8_LDA(At, 0, 1); PG8_STAGE(PG8_SB(0, 0), b2, voffB); PG8_STAGE(PG8_SB(0, 1), b2 + hstepB, voffB); PG8_STAGE(PG8_SA(0, 0), a2, voffA);
.LBB0_506:
	ds_read_b128 v[144:147], v151
	ds_read_b128 v[156:159], v151 offset:1024
	ds_read_b128 v[160:163], v151 offset:2048
	ds_read_b128 v[164:167], v151 offset:3072
	ds_read_b128 v[168:171], v152
	ds_read_b128 v[172:175], v152 offset:1024
	ds_read_b128 v[176:179], v152 offset:2048
	ds_read_b128 v[180:183], v152 offset:3072
	s_add_u32 s28, s26, 0xfff00080
	s_addc_u32 s29, s27, -1
	s_cmp_eq_u32 s50, 60
	s_cselect_b32 s31, s19, s29
	s_cselect_b32 s30, s25, s28
	s_cselect_b32 s29, s3, s49
	s_cselect_b32 s28, s47, s48
	v_lshl_add_u64 v[192:193], s[26:27], 0, v[136:137]
	s_add_i32 m0, s34, 0xc000
	ds_read_b128 v[184:187], v153
	ds_read_b128 v[188:191], v153 offset:1024
	ds_read_b128 v[198:201], v153 offset:2048
	ds_read_b128 v[202:205], v153 offset:3072
	ds_read_b128 v[216:219], v153 offset:4096
	ds_read_b128 v[220:223], v153 offset:5120
	ds_read_b128 v[224:227], v153 offset:6144
	ds_read_b128 v[228:231], v153 offset:7168
	global_load_lds_dwordx4 v[192:193], off
	v_lshl_add_u64 v[192:193], s[26:27], 0, v[138:139]
	s_add_i32 m0, s34, 0xe000
	s_nop 0
	global_load_lds_dwordx4 v[192:193], off
	s_nop 0
	s_waitcnt vmcnt(8)
	s_waitcnt lgkmcnt(0)
	s_setprio 1
	s_barrier
	v_mfma_f32_16x16x32_bf16 v[124:127], v[144:147], v[184:187], v[124:127]
	v_mfma_f32_16x16x32_bf16 v[120:123], v[160:163], v[184:187], v[120:123]
	v_mfma_f32_16x16x32_bf16 v[108:111], v[144:147], v[198:201], v[108:111]
	v_mfma_f32_16x16x32_bf16 v[104:107], v[160:163], v[198:201], v[104:107]
	v_mfma_f32_16x16x32_bf16 v[92:95], v[144:147], v[216:219], v[92:95]
	v_mfma_f32_16x16x32_bf16 v[88:91], v[160:163], v[216:219], v[88:91]
	v_mfma_f32_16x16x32_bf16 v[76:79], v[144:147], v[224:227], v[76:79]
	v_mfma_f32_16x16x32_bf16 v[72:75], v[160:163], v[224:227], v[72:75]
	v_mfma_f32_16x16x32_bf16 v[124:127], v[156:159], v[188:191], v[124:127]
	v_mfma_f32_16x16x32_bf16 v[120:123], v[164:167], v[188:191], v[120:123]
	v_mfma_f32_16x16x32_bf16 v[108:111], v[156:159], v[202:205], v[108:111]
	v_mfma_f32_16x16x32_bf16 v[104:107], v[164:167], v[202:205], v[104:107]
	v_mfma_f32_16x16x32_bf16 v[92:95], v[156:159], v[220:223], v[92:95]
	v_mfma_f32_16x16x32_bf16 v[88:91], v[164:167], v[220:223], v[88:91]
	v_mfma_f32_16x16x32_bf16 v[76:79], v[156:159], v[228:231], v[76:79]
	v_mfma_f32_16x16x32_bf16 v[72:75], v[164:167], v[228:231], v[72:75]
	v_mfma_f32_16x16x32_bf16 v[116:119], v[168:171], v[184:187], v[116:119]
	v_mfma_f32_16x16x32_bf16 v[112:115], v[176:179], v[184:187], v[112:115]
	v_mfma_f32_16x16x32_bf16 v[100:103], v[168:171], v[198:201], v[100:103]
	v_mfma_f32_16x16x32_bf16 v[96:99], v[176:179], v[198:201], v[96:99]
	v_mfma_f32_16x16x32_bf16 v[84:87], v[168:171], v[216:219], v[84:87]
	v_mfma_f32_16x16x32_bf16 v[80:83], v[176:179], v[216:219], v[80:83]
	v_mfma_f32_16x16x32_bf16 v[68:71], v[168:171], v[224:227], v[68:71]
	v_mfma_f32_16x16x32_bf16 v[64:67], v[176:179], v[224:227], v[64:67]
	v_mfma_f32_16x16x32_bf16 v[116:119], v[172:175], v[188:191], v[116:119]
	v_mfma_f32_16x16x32_bf16 v[112:115], v[180:183], v[188:191], v[112:115]
	v_mfma_f32_16x16x32_bf16 v[100:103], v[172:175], v[202:205], v[100:103]
	v_mfma_f32_16x16x32_bf16 v[96:99], v[180:183], v[202:205], v[96:99]
	v_mfma_f32_16x16x32_bf16 v[84:87], v[172:175], v[220:223], v[84:87]
	v_mfma_f32_16x16x32_bf16 v[80:83], v[180:183], v[220:223], v[80:83]
	v_mfma_f32_16x16x32_bf16 v[68:71], v[172:175], v[228:231], v[68:71]
	v_mfma_f32_16x16x32_bf16 v[64:67], v[180:183], v[228:231], v[64:67]
	s_barrier
	s_setprio 0
	s_add_i32 s51, s44, s33
	v_lshl_add_u64 v[192:193], s[28:29], 0, v[130:131]
	s_mov_b32 m0, s51
	ds_read_b128 v[184:187], v153 offset:16384
	ds_read_b128 v[188:191], v153 offset:17408
	ds_read_b128 v[198:201], v153 offset:18432
	ds_read_b128 v[202:205], v153 offset:19456
	ds_read_b128 v[216:219], v153 offset:20480
	ds_read_b128 v[220:223], v153 offset:21504
	ds_read_b128 v[224:227], v153 offset:22528
	ds_read_b128 v[228:231], v153 offset:23552
	global_load_lds_dwordx4 v[192:193], off
	s_add_i32 m0, s51, 0x2000
	s_add_u32 s52, s28, 0x100000
	v_lshl_add_u64 v[206:207], s[28:29], 0, v[134:135]
	s_addc_u32 s53, s29, 0
	s_add_i32 s51, s45, s33
	global_load_lds_dwordx4 v[206:207], off
	v_lshl_add_u64 v[210:211], s[52:53], 0, v[130:131]
	s_mov_b32 m0, s51
	v_lshl_add_u64 v[232:233], s[30:31], 0, v[132:133]
	global_load_lds_dwordx4 v[210:211], off
	v_lshl_add_u64 v[210:211], s[52:53], 0, v[134:135]
	s_add_i32 m0, s51, 0x2000
	s_nop 0
	global_load_lds_dwordx4 v[210:211], off
	v_lshl_add_u64 v[210:211], s[30:31], 0, v[128:129]
	s_mov_b32 m0, s34
	s_nop 0
	global_load_lds_dwordx4 v[210:211], off
	s_mov_b32 m0, s35
	s_nop 0
	global_load_lds_dwordx4 v[232:233], off
	s_waitcnt vmcnt(8)
	s_waitcnt lgkmcnt(0)
	s_setprio 1
	s_barrier
; #define PG8_STAGE(bufoff, gbase, voff) do { _Pragma("unroll") for (int _i = 0; _i < 2; ++_i) \
;         __builtin_amdgcn_global_load_lds((const unsigned*)((const char*)(gbase) + (voff)[_i]), (LAS unsigned*)(lds + (bufoff) + ldsw + _i * 8192), 16, 0, 0); } while (0)
; #define PG8_LDA(dst, b, h) do { _Pragma("unroll") for (int m = 0; m < 4; ++m) _Pragma("unroll") for (int k = 0; k < 2; ++k) dst[m][k] = *(const LAS bf16x8*)(lds + PG8_SA(b, h) + aoff + m * 2048 + k * 1024); } while (0)
; #define PG8_LDB(dst, b, h) do { _Pragma("unroll") for (int n = 0; n < 2; ++n) _Pragma("unroll") for (int k = 0; k < 2; ++k) dst[n][k] = *(const LAS bf16x8*)(lds + PG8_SB(b, h) + boff + n * 2048 + k * 1024); } while (0)
; #define PG8_MMA(ai, bj, At, Bt) do { __builtin_amdgcn_s_setprio(1); _Pragma("unroll") for (int m = 0; m < 4; ++m) _Pragma("unroll") for (int n = 0; n < 2; ++n) _Pragma("unroll") for (int k = 0; k < 2; ++k) \
;         acc[ai][bj][m][n] = __builtin_amdgcn_mfma_f32_16x16x32_bf16(Bt[n][k], At[m][k], acc[ai][bj][m][n], 0, 0, 0); __builtin_amdgcn_s_setprio(0); } while (0)
; #define PG8_WAIT_V(n) asm volatile("s_waitcnt vmcnt(" #n ")" ::: "memory")
; #define PG8_WAIT_L(n) asm volatile("s_waitcnt lgkmcnt(" #n ")" ::: "memory")
; #define PG8_BAR __builtin_amdgcn_s_barrier()
; #define PG8_SCHED __builtin_amdgcn_sched_barrier(0)
; template <class Epi, bool ALIGN_EPI, bool SP2 = PG8_SP2_DEFAULT>
; __device__ __forceinline__ void gemm_phase(LAS unsigned char* lds, const Gemm g, const StaticOrder& S, const Epi& E) {
;     ...
;             PG8_WAIT_V(8); PG8_WAIT_L(0); PG8_BAR; PG8_MMA(1, 0, At, B0); PG8_MMA(1, 1, At, B1); PG8_BAR; PG8_SCHED;
;             PG8_LDB(B0, 1, 0); PG8_LDB(B1, 1, 1); PG8_SCHED; PG8_LDA(At, 1, 0); PG8_STAGE(PG8_SA(0, 1), a2 + hstepA, voffA);
;             PG8_WAIT_V(8); PG8_WAIT_L(0); PG8_BAR; PG8_MMA(0, 0, At, B0); PG8_MMA(0, 1, At, B1); PG8_BAR; PG8_SCHED;
	v_mfma_f32_16x16x32_bf16 v[60:63], v[144:147], v[184:187], v[60:63]
	v_mfma_f32_16x16x32_bf16 v[56:59], v[160:163], v[184:187], v[56:59]
	v_mfma_f32_16x16x32_bf16 v[44:47], v[144:147], v[198:201], v[44:47]
	v_mfma_f32_16x16x32_bf16 v[40:43], v[160:163], v[198:201], v[40:43]
	v_mfma_f32_16x16x32_bf16 v[28:31], v[144:147], v[216:219], v[28:31]
	v_mfma_f32_16x16x32_bf16 v[24:27], v[160:163], v[216:219], v[24:27]
	v_mfma_f32_16x16x32_bf16 v[12:15], v[144:147], v[224:227], v[12:15]
	v_mfma_f32_16x16x32_bf16 v[8:11], v[160:163], v[224:227], v[8:11]
	v_mfma_f32_16x16x32_bf16 v[60:63], v[156:159], v[188:191], v[60:63]
	v_mfma_f32_16x16x32_bf16 v[56:59], v[164:167], v[188:191], v[56:59]
	v_mfma_f32_16x16x32_bf16 v[44:47], v[156:159], v[202:205], v[44:47]
	v_mfma_f32_16x16x32_bf16 v[40:43], v[164:167], v[202:205], v[40:43]
	v_mfma_f32_16x16x32_bf16 v[28:31], v[156:159], v[220:223], v[28:31]
	v_mfma_f32_16x16x32_bf16 v[24:27], v[164:167], v[220:223], v[24:27]
	v_mfma_f32_16x16x32_bf16 v[12:15], v[156:159], v[228:231], v[12:15]
	v_mfma_f32_16x16x32_bf16 v[8:11], v[164:167], v[228:231], v[8:11]
	v_mfma_f32_16x16x32_bf16 v[52:55], v[168:171], v[184:187], v[52:55]
	v_mfma_f32_16x16x32_bf16 v[48:51], v[176:179], v[184:187], v[48:51]
	v_mfma_f32_16x16x32_bf16 v[36:39], v[168:171], v[198:201], v[36:39]
	v_mfma_f32_16x16x32_bf16 v[32:35], v[176:179], v[198:201], v[32:35]
	v_mfma_f32_16x16x32_bf16 v[20:23], v[168:171], v[216:219], v[20:23]
	v_mfma_f32_16x16x32_bf16 v[16:19], v[176:179], v[216:219], v[16:19]
	v_mfma_f32_16x16x32_bf16 v[4:7], v[168:171], v[224:227], v[4:7]
	v_mfma_f32_16x16x32_bf16 v[0:3], v[176:179], v[224:227], v[0:3]
	v_mfma_f32_16x16x32_bf16 v[52:55], v[172:175], v[188:191], v[52:55]
	v_mfma_f32_16x16x32_bf16 v[48:51], v[180:183], v[188:191], v[48:51]
	v_mfma_f32_16x16x32_bf16 v[36:39], v[172:175], v[202:205], v[36:39]
	v_mfma_f32_16x16x32_bf16 v[32:35], v[180:183], v[202:205], v[32:35]
	v_mfma_f32_16x16x32_bf16 v[20:23], v[172:175], v[220:223], v[20:23]
	v_mfma_f32_16x16x32_bf16 v[16:19], v[180:183], v[220:223], v[16:19]
	v_mfma_f32_16x16x32_bf16 v[4:7], v[172:175], v[228:231], v[4:7]
	v_mfma_f32_16x16x32_bf16 v[0:3], v[180:183], v[228:231], v[0:3]
	s_barrier
	s_setprio 0
	s_add_i32 s51, 0, 0x18000
	v_add_u32_e32 v155, s51, v149
	s_add_i32 s52, 0, 0x1c000
	ds_read_b128 v[144:147], v155
	ds_read_b128 v[156:159], v155 offset:1024
	ds_read_b128 v[160:163], v155 offset:2048
	ds_read_b128 v[164:167], v155 offset:3072
	v_add_u32_e32 v155, s52, v149
	ds_read_b128 v[168:171], v155
	ds_read_b128 v[172:175], v155 offset:1024
	ds_read_b128 v[176:179], v155 offset:2048
	ds_read_b128 v[180:183], v155 offset:3072
	s_add_u32 s30, s30, 0x100000
	s_addc_u32 s31, s31, 0
	s_mov_b32 m0, s36
	v_lshl_add_u64 v[234:235], s[30:31], 0, v[128:129]
	ds_read_b128 v[184:187], v153 offset:32768
	ds_read_b128 v[188:191], v153 offset:33792
	ds_read_b128 v[198:201], v153 offset:34816
	ds_read_b128 v[202:205], v153 offset:35840
	ds_read_b128 v[216:219], v153 offset:36864
	ds_read_b128 v[220:223], v153 offset:37888
	ds_read_b128 v[224:227], v153 offset:38912
	ds_read_b128 v[228:231], v153 offset:39936
	global_load_lds_dwordx4 v[234:235], off
	v_lshl_add_u64 v[234:235], s[30:31], 0, v[132:133]
	s_mov_b32 m0, s37
	s_nop 0
	global_load_lds_dwordx4 v[234:235], off
	s_waitcnt vmcnt(8)
	s_waitcnt lgkmcnt(0)
	s_setprio 1
	s_barrier
	v_mfma_f32_16x16x32_bf16 v[124:127], v[144:147], v[184:187], v[124:127]
	v_mfma_f32_16x16x32_bf16 v[120:123], v[160:163], v[184:187], v[120:123]
	v_mfma_f32_16x16x32_bf16 v[108:111], v[144:147], v[198:201], v[108:111]
	v_mfma_f32_16x16x32_bf16 v[104:107], v[160:163], v[198:201], v[104:107]
	v_mfma_f32_16x16x32_bf16 v[92:95], v[144:147], v[216:219], v[92:95]
	v_mfma_f32_16x16x32_bf16 v[88:91], v[160:163], v[216:219], v[88:91]
	v_mfma_f32_16x16x32_bf16 v[76:79], v[144:147], v[224:227], v[76:79]
	v_mfma_f32_16x16x32_bf16 v[72:75], v[160:163], v[224:227], v[72:75]
	v_mfma_f32_16x16x32_bf16 v[124:127], v[156:159], v[188:191], v[124:127]
	v_mfma_f32_16x16x32_bf16 v[120:123], v[164:167], v[188:191], v[120:123]
	v_mfma_f32_16x16x32_bf16 v[108:111], v[156:159], v[202:205], v[108:111]
	v_mfma_f32_16x16x32_bf16 v[104:107], v[164:167], v[202:205], v[104:107]
	v_mfma_f32_16x16x32_bf16 v[92:95], v[156:159], v[220:223], v[92:95]
	v_mfma_f32_16x16x32_bf16 v[88:91], v[164:167], v[220:223], v[88:91]
	v_mfma_f32_16x16x32_bf16 v[76:79], v[156:159], v[228:231], v[76:79]
	v_mfma_f32_16x16x32_bf16 v[72:75], v[164:167], v[228:231], v[72:75]
	v_mfma_f32_16x16x32_bf16 v[116:119], v[168:171], v[184:187], v[116:119]
	v_mfma_f32_16x16x32_bf16 v[112:115], v[176:179], v[184:187], v[112:115]
	v_mfma_f32_16x16x32_bf16 v[100:103], v[168:171], v[198:201], v[100:103]
	v_mfma_f32_16x16x32_bf16 v[96:99], v[176:179], v[198:201], v[96:99]
	v_mfma_f32_16x16x32_bf16 v[84:87], v[168:171], v[216:219], v[84:87]
	v_mfma_f32_16x16x32_bf16 v[80:83], v[176:179], v[216:219], v[80:83]
	v_mfma_f32_16x16x32_bf16 v[68:71], v[168:171], v[224:227], v[68:71]
	v_mfma_f32_16x16x32_bf16 v[64:67], v[176:179], v[224:227], v[64:67]
	v_mfma_f32_16x16x32_bf16 v[116:119], v[172:175], v[188:191], v[116:119]
	v_mfma_f32_16x16x32_bf16 v[112:115], v[180:183], v[188:191], v[112:115]
	v_mfma_f32_16x16x32_bf16 v[100:103], v[172:175], v[202:205], v[100:103]
	v_mfma_f32_16x16x32_bf16 v[96:99], v[180:183], v[202:205], v[96:99]
	v_mfma_f32_16x16x32_bf16 v[84:87], v[172:175], v[220:223], v[84:87]
	v_mfma_f32_16x16x32_bf16 v[80:83], v[180:183], v[220:223], v[80:83]
	v_mfma_f32_16x16x32_bf16 v[68:71], v[172:175], v[228:231], v[68:71]
	v_mfma_f32_16x16x32_bf16 v[64:67], v[180:183], v[228:231], v[64:67]
	s_barrier
; #define PG8_STAGE(bufoff, gbase, voff) do { _Pragma("unroll") for (int _i = 0; _i < 2; ++_i) \
;         __builtin_amdgcn_global_load_lds((const unsigned*)((const char*)(gbase) + (voff)[_i]), (LAS unsigned*)(lds + (bufoff) + ldsw + _i * 8192), 16, 0, 0); } while (0)
; #define PG8_LDA(dst, b, h) do { _Pragma("unroll") for (int m = 0; m < 4; ++m) _Pragma("unroll") for (int k = 0; k < 2; ++k) dst[m][k] = *(const LAS bf16x8*)(lds + PG8_SA(b, h) + aoff + m * 2048 + k * 1024); } while (0)
; #define PG8_MMA(ai, bj, At, Bt) do { __builtin_amdgcn_s_setprio(1); _Pragma("unroll") for (int m = 0; m < 4; ++m) _Pragma("unroll") for (int n = 0; n < 2; ++n) _Pragma("unroll") for (int k = 0; k < 2; ++k) \
;         acc[ai][bj][m][n] = __builtin_amdgcn_mfma_f32_16x16x32_bf16(Bt[n][k], At[m][k], acc[ai][bj][m][n], 0, 0, 0); __builtin_amdgcn_s_setprio(0); } while (0)
; #define PG8_WAIT_V(n) asm volatile("s_waitcnt vmcnt(" #n ")" ::: "memory")
; #define PG8_WAIT_L(n) asm volatile("s_waitcnt lgkmcnt(" #n ")" ::: "memory")
; #define PG8_BAR __builtin_amdgcn_s_barrier()
; #define PG8_SCHED __builtin_amdgcn_sched_barrier(0)
; template <class Epi, bool ALIGN_EPI, bool SP2 = PG8_SP2_DEFAULT>
; __device__ __forceinline__ void gemm_phase(LAS unsigned char* lds, const Gemm g, const StaticOrder& S, const Epi& E) {
;     ...
;         for (int t = 0; t < nt; t += 2) {
;     ...
;             PG8_LDA(At, 1, 1); PG8_STAGE(PG8_SB(1, 0), b3, voffB); PG8_STAGE(PG8_SB(1, 1), b3 + hstepB, voffB); PG8_STAGE(PG8_SA(1, 0), a3, voffA);
;             PG8_WAIT_V(8); PG8_WAIT_L(0); PG8_BAR; PG8_MMA(1, 0, At, B0); PG8_MMA(1, 1, At, B1); PG8_BAR; PG8_SCHED;
;     ...
;         if constexpr (ALIGN_EPI) { if (wr == 0) PG8_BAR; }
	s_setprio 0
	s_add_i32 s30, s51, s33
	v_lshl_add_u64 v[192:193], v[192:193], 0, s[14:15]
	s_mov_b32 m0, s30
	ds_read_b128 v[184:187], v153 offset:49152
	ds_read_b128 v[188:191], v153 offset:50176
	ds_read_b128 v[198:201], v153 offset:51200
	ds_read_b128 v[202:205], v153 offset:52224
	ds_read_b128 v[216:219], v153 offset:53248
	ds_read_b128 v[220:223], v153 offset:54272
	ds_read_b128 v[224:227], v153 offset:55296
	ds_read_b128 v[228:231], v153 offset:56320
	global_load_lds_dwordx4 v[192:193], off
	s_add_i32 m0, s30, 0x2000
	s_add_u32 s28, s28, 0x100080
	v_lshl_add_u64 v[192:193], v[206:207], 0, s[14:15]
	s_addc_u32 s29, s29, 0
	s_add_i32 s30, s52, s33
	global_load_lds_dwordx4 v[192:193], off
	v_lshl_add_u64 v[192:193], s[28:29], 0, v[130:131]
	s_mov_b32 m0, s30
	s_nop 0
	global_load_lds_dwordx4 v[192:193], off
	v_lshl_add_u64 v[192:193], s[28:29], 0, v[134:135]
	s_add_i32 m0, s30, 0x2000
	s_nop 0
	global_load_lds_dwordx4 v[192:193], off
	v_lshl_add_u64 v[192:193], v[210:211], 0, s[14:15]
	s_mov_b32 m0, s39
	s_nop 0
	global_load_lds_dwordx4 v[192:193], off
	v_lshl_add_u64 v[192:193], v[232:233], 0, s[14:15]
	s_mov_b32 m0, s40
	s_nop 0
	global_load_lds_dwordx4 v[192:193], off
	s_nop 0
	s_waitcnt vmcnt(8)
	s_waitcnt lgkmcnt(0)
	s_setprio 1
	s_barrier
	v_mfma_f32_16x16x32_bf16 v[60:63], v[144:147], v[184:187], v[60:63]
	v_mfma_f32_16x16x32_bf16 v[56:59], v[160:163], v[184:187], v[56:59]
	v_mfma_f32_16x16x32_bf16 v[44:47], v[144:147], v[198:201], v[44:47]
	v_mfma_f32_16x16x32_bf16 v[40:43], v[160:163], v[198:201], v[40:43]
	v_mfma_f32_16x16x32_bf16 v[28:31], v[144:147], v[216:219], v[28:31]
	v_mfma_f32_16x16x32_bf16 v[24:27], v[160:163], v[216:219], v[24:27]
	v_mfma_f32_16x16x32_bf16 v[12:15], v[144:147], v[224:227], v[12:15]
	v_mfma_f32_16x16x32_bf16 v[8:11], v[160:163], v[224:227], v[8:11]
	v_mfma_f32_16x16x32_bf16 v[60:63], v[156:159], v[188:191], v[60:63]
	v_mfma_f32_16x16x32_bf16 v[56:59], v[164:167], v[188:191], v[56:59]
	v_mfma_f32_16x16x32_bf16 v[44:47], v[156:159], v[202:205], v[44:47]
	v_mfma_f32_16x16x32_bf16 v[40:43], v[164:167], v[202:205], v[40:43]
	v_mfma_f32_16x16x32_bf16 v[28:31], v[156:159], v[220:223], v[28:31]
	v_mfma_f32_16x16x32_bf16 v[24:27], v[164:167], v[220:223], v[24:27]
	v_mfma_f32_16x16x32_bf16 v[12:15], v[156:159], v[228:231], v[12:15]
	v_mfma_f32_16x16x32_bf16 v[8:11], v[164:167], v[228:231], v[8:11]
	v_mfma_f32_16x16x32_bf16 v[52:55], v[168:171], v[184:187], v[52:55]
	v_mfma_f32_16x16x32_bf16 v[48:51], v[176:179], v[184:187], v[48:51]
	v_mfma_f32_16x16x32_bf16 v[36:39], v[168:171], v[198:201], v[36:39]
	v_mfma_f32_16x16x32_bf16 v[32:35], v[176:179], v[198:201], v[32:35]
	v_mfma_f32_16x16x32_bf16 v[20:23], v[168:171], v[216:219], v[20:23]
	v_mfma_f32_16x16x32_bf16 v[16:19], v[176:179], v[216:219], v[16:19]
	v_mfma_f32_16x16x32_bf16 v[4:7], v[168:171], v[224:227], v[4:7]
	v_mfma_f32_16x16x32_bf16 v[0:3], v[176:179], v[224:227], v[0:3]
	v_mfma_f32_16x16x32_bf16 v[52:55], v[172:175], v[188:191], v[52:55]
	v_mfma_f32_16x16x32_bf16 v[48:51], v[180:183], v[188:191], v[48:51]
	v_mfma_f32_16x16x32_bf16 v[36:39], v[172:175], v[202:205], v[36:39]
	v_mfma_f32_16x16x32_bf16 v[32:35], v[180:183], v[202:205], v[32:35]
	v_mfma_f32_16x16x32_bf16 v[20:23], v[172:175], v[220:223], v[20:23]
	v_mfma_f32_16x16x32_bf16 v[16:19], v[180:183], v[220:223], v[16:19]
	v_mfma_f32_16x16x32_bf16 v[4:7], v[172:175], v[228:231], v[4:7]
	v_mfma_f32_16x16x32_bf16 v[0:3], v[180:183], v[228:231], v[0:3]
	s_barrier
	s_setprio 0
	s_add_i32 s50, s50, 2
	s_add_u32 s26, s26, 0x100
	s_addc_u32 s27, s27, 0
	s_add_u32 s48, s48, 0x100
	s_addc_u32 s49, s49, 0
	s_cmp_gt_u32 s50, 61
	s_cbranch_scc0 .LBB0_506
	s_and_b64 vcc, exec, s[16:17]
	s_cbranch_vccz .LBB0_509
	s_barrier

; #define PG8_STAGE(bufoff, gbase, voff) do { _Pragma("unroll") for (int _i = 0; _i < 2; ++_i) \
;         __builtin_amdgcn_global_load_lds((const unsigned*)((const char*)(gbase) + (voff)[_i]), (LAS unsigned*)(lds + (bufoff) + ldsw + _i * 8192), 16, 0, 0); } while (0)
; #define PG8_LDA(dst, b, h) do { _Pragma("unroll") for (int m = 0; m < 4; ++m) _Pragma("unroll") for (int k = 0; k < 2; ++k) dst[m][k] = *(const LAS bf16x8*)(lds + PG8_SA(b, h) + aoff + m * 2048 + k * 1024); } while (0)
; #define PG8_LDB(dst, b, h) do { _Pragma("unroll") for (int n = 0; n < 2; ++n) _Pragma("unroll") for (int k = 0; k < 2; ++k) dst[n][k] = *(const LAS bf16x8*)(lds + PG8_SB(b, h) + boff + n * 2048 + k * 1024); } while (0)
; #define PG8_MMA(ai, bj, At, Bt) do { __builtin_amdgcn_s_setprio(1); _Pragma("unroll") for (int m = 0; m < 4; ++m) _Pragma("unroll") for (int n = 0; n < 2; ++n) _Pragma("unroll") for (int k = 0; k < 2; ++k) \
;         acc[ai][bj][m][n] = __builtin_amdgcn_mfma_f32_16x16x32_bf16(Bt[n][k], At[m][k], acc[ai][bj][m][n], 0, 0, 0); __builtin_amdgcn_s_setprio(0); } while (0)
; #define PG8_WAIT_V(n) asm volatile("s_waitcnt vmcnt(" #n ")" ::: "memory")
; #define PG8_WAIT_L(n) asm volatile("s_waitcnt lgkmcnt(" #n ")" ::: "memory")
; #define PG8_BAR __builtin_amdgcn_s_barrier()
; #define PG8_SCHED __builtin_amdgcn_sched_barrier(0)
; template <class Epi, bool ALIGN_EPI, bool SP2 = PG8_SP2_DEFAULT>
; __device__ __forceinline__ void gemm_phase(LAS unsigned char* lds, const Gemm g, const StaticOrder& S, const Epi& E) {
;     ...
;             const bool last = (t == nt - 2);
;             const char* a1 = cA + (size_t)(t + 1) * kstep;
;             const char* a2 = last ? nA : cA + (size_t)(t + 2) * kstep; const char* b2 = last ? nB : cB + (size_t)(t + 2) * kstep;
;             const char* a3 = a2 + kstep; const char* b3 = b2 + kstep;
;             if constexpr (SP2) {
;             PG8_LDB(B0, 0, 0); PG8_LDB(B1, 0, 1); PG8_SCHED; PG8_LDA(At, 0, 0); PG8_STAGE(PG8_SA(1, 1), a1 + hstepA, voffA);
;             PG8_WAIT_V(8); PG8_WAIT_L(0); PG8_BAR; PG8_MMA(0, 0, At, B0); PG8_MMA(0, 1, At, B1); PG8_BAR; PG8_SCHED;
;             PG8_LDA(At, 0, 1); PG8_STAGE(PG8_SB(0, 0), b2, voffB); PG8_STAGE(PG8_SB(0, 1), b2 + hstepB, voffB); PG8_STAGE(PG8_SA(0, 0), a2, voffA);
.LBB0_598:
	ds_read_b128 v[146:149], v155
	ds_read_b128 v[160:163], v155 offset:1024
	ds_read_b128 v[164:167], v155 offset:2048
	ds_read_b128 v[168:171], v155 offset:3072
	ds_read_b128 v[172:175], v156
	ds_read_b128 v[176:179], v156 offset:1024
	ds_read_b128 v[180:183], v156 offset:2048
	ds_read_b128 v[184:187], v156 offset:3072
	s_add_u32 s24, s22, 0xfff00080
	s_addc_u32 s25, s23, -1
	s_cmp_eq_u32 s47, 60
	s_cselect_b32 s27, s3, s25
	s_cselect_b32 s26, s7, s24
	s_cselect_b32 s25, s9, s45
	s_cselect_b32 s24, s17, s44
	v_lshl_add_u64 v[192:193], s[22:23], 0, v[138:139]
	s_add_i32 m0, s30, 0xc000
	ds_read_b128 v[188:191], v157
	ds_read_b128 v[198:201], v157 offset:1024
	ds_read_b128 v[202:205], v157 offset:2048
	ds_read_b128 v[214:217], v157 offset:3072
	ds_read_b128 v[218:221], v157 offset:4096
	ds_read_b128 v[222:225], v157 offset:5120
	ds_read_b128 v[226:229], v157 offset:6144
	ds_read_b128 v[230:233], v157 offset:7168
	global_load_lds_dwordx4 v[192:193], off
	v_lshl_add_u64 v[192:193], s[22:23], 0, v[140:141]
	s_add_i32 m0, s30, 0xe000
	s_nop 0
	global_load_lds_dwordx4 v[192:193], off
	s_waitcnt vmcnt(8)
	s_waitcnt lgkmcnt(0)
	s_setprio 1
	s_barrier
	v_mfma_f32_16x16x32_bf16 v[124:127], v[146:149], v[188:191], v[124:127]
	v_mfma_f32_16x16x32_bf16 v[120:123], v[164:167], v[188:191], v[120:123]
	v_mfma_f32_16x16x32_bf16 v[108:111], v[146:149], v[202:205], v[108:111]
	v_mfma_f32_16x16x32_bf16 v[104:107], v[164:167], v[202:205], v[104:107]
	v_mfma_f32_16x16x32_bf16 v[92:95], v[146:149], v[218:221], v[92:95]
	v_mfma_f32_16x16x32_bf16 v[88:91], v[164:167], v[218:221], v[88:91]
	v_mfma_f32_16x16x32_bf16 v[76:79], v[146:149], v[226:229], v[76:79]
	v_mfma_f32_16x16x32_bf16 v[72:75], v[164:167], v[226:229], v[72:75]
	v_mfma_f32_16x16x32_bf16 v[124:127], v[160:163], v[198:201], v[124:127]
	v_mfma_f32_16x16x32_bf16 v[120:123], v[168:171], v[198:201], v[120:123]
	v_mfma_f32_16x16x32_bf16 v[108:111], v[160:163], v[214:217], v[108:111]
	v_mfma_f32_16x16x32_bf16 v[104:107], v[168:171], v[214:217], v[104:107]
	v_mfma_f32_16x16x32_bf16 v[92:95], v[160:163], v[222:225], v[92:95]
	v_mfma_f32_16x16x32_bf16 v[88:91], v[168:171], v[222:225], v[88:91]
	v_mfma_f32_16x16x32_bf16 v[76:79], v[160:163], v[230:233], v[76:79]
	v_mfma_f32_16x16x32_bf16 v[72:75], v[168:171], v[230:233], v[72:75]
	v_mfma_f32_16x16x32_bf16 v[116:119], v[172:175], v[188:191], v[116:119]
	v_mfma_f32_16x16x32_bf16 v[112:115], v[180:183], v[188:191], v[112:115]
	v_mfma_f32_16x16x32_bf16 v[100:103], v[172:175], v[202:205], v[100:103]
	v_mfma_f32_16x16x32_bf16 v[96:99], v[180:183], v[202:205], v[96:99]
	v_mfma_f32_16x16x32_bf16 v[84:87], v[172:175], v[218:221], v[84:87]
	v_mfma_f32_16x16x32_bf16 v[80:83], v[180:183], v[218:221], v[80:83]
	v_mfma_f32_16x16x32_bf16 v[68:71], v[172:175], v[226:229], v[68:71]
	v_mfma_f32_16x16x32_bf16 v[64:67], v[180:183], v[226:229], v[64:67]
	v_mfma_f32_16x16x32_bf16 v[116:119], v[176:179], v[198:201], v[116:119]
	v_mfma_f32_16x16x32_bf16 v[112:115], v[184:187], v[198:201], v[112:115]
	v_mfma_f32_16x16x32_bf16 v[100:103], v[176:179], v[214:217], v[100:103]
	v_mfma_f32_16x16x32_bf16 v[96:99], v[184:187], v[214:217], v[96:99]
	v_mfma_f32_16x16x32_bf16 v[84:87], v[176:179], v[222:225], v[84:87]
	v_mfma_f32_16x16x32_bf16 v[80:83], v[184:187], v[222:225], v[80:83]
	v_mfma_f32_16x16x32_bf16 v[68:71], v[176:179], v[230:233], v[68:71]
	v_mfma_f32_16x16x32_bf16 v[64:67], v[184:187], v[230:233], v[64:67]
	s_barrier
	s_setprio 0
	s_add_i32 s48, s41, s29
	v_lshl_add_u64 v[192:193], s[24:25], 0, v[130:131]
	s_mov_b32 m0, s48
	ds_read_b128 v[188:191], v157 offset:16384
	ds_read_b128 v[198:201], v157 offset:17408
	ds_read_b128 v[202:205], v157 offset:18432
	ds_read_b128 v[214:217], v157 offset:19456
	ds_read_b128 v[218:221], v157 offset:20480
	ds_read_b128 v[222:225], v157 offset:21504
	ds_read_b128 v[226:229], v157 offset:22528
	ds_read_b128 v[230:233], v157 offset:23552
	global_load_lds_dwordx4 v[192:193], off
	s_add_i32 m0, s48, 0x2000
	s_add_u32 s48, s24, 0x100000
	v_lshl_add_u64 v[206:207], s[24:25], 0, v[134:135]
	s_addc_u32 s49, s25, 0
	s_add_i32 s50, s42, s29
	global_load_lds_dwordx4 v[206:207], off
	v_lshl_add_u64 v[210:211], s[48:49], 0, v[130:131]
	s_mov_b32 m0, s50
	v_lshl_add_u64 v[234:235], s[26:27], 0, v[132:133]
	global_load_lds_dwordx4 v[210:211], off
	v_lshl_add_u64 v[210:211], s[48:49], 0, v[134:135]
	s_add_i32 m0, s50, 0x2000
	s_nop 0
	global_load_lds_dwordx4 v[210:211], off
	v_lshl_add_u64 v[210:211], s[26:27], 0, v[128:129]
	s_mov_b32 m0, s30
	s_nop 0
	global_load_lds_dwordx4 v[210:211], off
	s_mov_b32 m0, s31
	s_nop 0
	global_load_lds_dwordx4 v[234:235], off
	s_waitcnt vmcnt(8)
	s_waitcnt lgkmcnt(0)
	s_setprio 1
	s_barrier
; #define PG8_STAGE(bufoff, gbase, voff) do { _Pragma("unroll") for (int _i = 0; _i < 2; ++_i) \
;         __builtin_amdgcn_global_load_lds((const unsigned*)((const char*)(gbase) + (voff)[_i]), (LAS unsigned*)(lds + (bufoff) + ldsw + _i * 8192), 16, 0, 0); } while (0)
; #define PG8_LDA(dst, b, h) do { _Pragma("unroll") for (int m = 0; m < 4; ++m) _Pragma("unroll") for (int k = 0; k < 2; ++k) dst[m][k] = *(const LAS bf16x8*)(lds + PG8_SA(b, h) + aoff + m * 2048 + k * 1024); } while (0)
; #define PG8_LDB(dst, b, h) do { _Pragma("unroll") for (int n = 0; n < 2; ++n) _Pragma("unroll") for (int k = 0; k < 2; ++k) dst[n][k] = *(const LAS bf16x8*)(lds + PG8_SB(b, h) + boff + n * 2048 + k * 1024); } while (0)
; #define PG8_MMA(ai, bj, At, Bt) do { __builtin_amdgcn_s_setprio(1); _Pragma("unroll") for (int m = 0; m < 4; ++m) _Pragma("unroll") for (int n = 0; n < 2; ++n) _Pragma("unroll") for (int k = 0; k < 2; ++k) \
;         acc[ai][bj][m][n] = __builtin_amdgcn_mfma_f32_16x16x32_bf16(Bt[n][k], At[m][k], acc[ai][bj][m][n], 0, 0, 0); __builtin_amdgcn_s_setprio(0); } while (0)
; #define PG8_WAIT_V(n) asm volatile("s_waitcnt vmcnt(" #n ")" ::: "memory")
; #define PG8_WAIT_L(n) asm volatile("s_waitcnt lgkmcnt(" #n ")" ::: "memory")
; #define PG8_BAR __builtin_amdgcn_s_barrier()
; #define PG8_SCHED __builtin_amdgcn_sched_barrier(0)
; template <class Epi, bool ALIGN_EPI, bool SP2 = PG8_SP2_DEFAULT>
; __device__ __forceinline__ void gemm_phase(LAS unsigned char* lds, const Gemm g, const StaticOrder& S, const Epi& E) {
;     ...
;             PG8_WAIT_V(8); PG8_WAIT_L(0); PG8_BAR; PG8_MMA(1, 0, At, B0); PG8_MMA(1, 1, At, B1); PG8_BAR; PG8_SCHED;
;             PG8_LDB(B0, 1, 0); PG8_LDB(B1, 1, 1); PG8_SCHED; PG8_LDA(At, 1, 0); PG8_STAGE(PG8_SA(0, 1), a2 + hstepA, voffA);
;             PG8_WAIT_V(8); PG8_WAIT_L(0); PG8_BAR; PG8_MMA(0, 0, At, B0); PG8_MMA(0, 1, At, B1); PG8_BAR; PG8_SCHED;
	v_mfma_f32_16x16x32_bf16 v[60:63], v[146:149], v[188:191], v[60:63]
	v_mfma_f32_16x16x32_bf16 v[56:59], v[164:167], v[188:191], v[56:59]
	v_mfma_f32_16x16x32_bf16 v[44:47], v[146:149], v[202:205], v[44:47]
	v_mfma_f32_16x16x32_bf16 v[40:43], v[164:167], v[202:205], v[40:43]
	v_mfma_f32_16x16x32_bf16 v[28:31], v[146:149], v[218:221], v[28:31]
	v_mfma_f32_16x16x32_bf16 v[24:27], v[164:167], v[218:221], v[24:27]
	v_mfma_f32_16x16x32_bf16 v[12:15], v[146:149], v[226:229], v[12:15]
	v_mfma_f32_16x16x32_bf16 v[8:11], v[164:167], v[226:229], v[8:11]
	v_mfma_f32_16x16x32_bf16 v[60:63], v[160:163], v[198:201], v[60:63]
	v_mfma_f32_16x16x32_bf16 v[56:59], v[168:171], v[198:201], v[56:59]
	v_mfma_f32_16x16x32_bf16 v[44:47], v[160:163], v[214:217], v[44:47]
	v_mfma_f32_16x16x32_bf16 v[40:43], v[168:171], v[214:217], v[40:43]
	v_mfma_f32_16x16x32_bf16 v[28:31], v[160:163], v[222:225], v[28:31]
	v_mfma_f32_16x16x32_bf16 v[24:27], v[168:171], v[222:225], v[24:27]
	v_mfma_f32_16x16x32_bf16 v[12:15], v[160:163], v[230:233], v[12:15]
	v_mfma_f32_16x16x32_bf16 v[8:11], v[168:171], v[230:233], v[8:11]
	v_mfma_f32_16x16x32_bf16 v[52:55], v[172:175], v[188:191], v[52:55]
	v_mfma_f32_16x16x32_bf16 v[48:51], v[180:183], v[188:191], v[48:51]
	v_mfma_f32_16x16x32_bf16 v[36:39], v[172:175], v[202:205], v[36:39]
	v_mfma_f32_16x16x32_bf16 v[32:35], v[180:183], v[202:205], v[32:35]
	v_mfma_f32_16x16x32_bf16 v[20:23], v[172:175], v[218:221], v[20:23]
	v_mfma_f32_16x16x32_bf16 v[16:19], v[180:183], v[218:221], v[16:19]
	v_mfma_f32_16x16x32_bf16 v[4:7], v[172:175], v[226:229], v[4:7]
	v_mfma_f32_16x16x32_bf16 v[0:3], v[180:183], v[226:229], v[0:3]
	v_mfma_f32_16x16x32_bf16 v[52:55], v[176:179], v[198:201], v[52:55]
	v_mfma_f32_16x16x32_bf16 v[48:51], v[184:187], v[198:201], v[48:51]
	v_mfma_f32_16x16x32_bf16 v[36:39], v[176:179], v[214:217], v[36:39]
	v_mfma_f32_16x16x32_bf16 v[32:35], v[184:187], v[214:217], v[32:35]
	v_mfma_f32_16x16x32_bf16 v[20:23], v[176:179], v[222:225], v[20:23]
	v_mfma_f32_16x16x32_bf16 v[16:19], v[184:187], v[222:225], v[16:19]
	v_mfma_f32_16x16x32_bf16 v[4:7], v[176:179], v[230:233], v[4:7]
	v_mfma_f32_16x16x32_bf16 v[0:3], v[184:187], v[230:233], v[0:3]
	s_barrier
	s_setprio 0
	s_add_i32 s48, 0, 0x18000
	v_add_u32_e32 v150, s48, v152
	s_add_i32 s49, 0, 0x1c000
	ds_read_b128 v[146:149], v150
	ds_read_b128 v[160:163], v150 offset:1024
	ds_read_b128 v[164:167], v150 offset:2048
	ds_read_b128 v[168:171], v150 offset:3072
	v_add_u32_e32 v150, s49, v152
	ds_read_b128 v[172:175], v150
	ds_read_b128 v[176:179], v150 offset:1024
	ds_read_b128 v[180:183], v150 offset:2048
	ds_read_b128 v[184:187], v150 offset:3072
	s_add_u32 s26, s26, 0x100000
	s_addc_u32 s27, s27, 0
	s_mov_b32 m0, s33
	v_lshl_add_u64 v[236:237], s[26:27], 0, v[128:129]
	ds_read_b128 v[188:191], v157 offset:32768
	ds_read_b128 v[198:201], v157 offset:33792
	ds_read_b128 v[202:205], v157 offset:34816
	ds_read_b128 v[214:217], v157 offset:35840
	ds_read_b128 v[218:221], v157 offset:36864
	ds_read_b128 v[222:225], v157 offset:37888
	ds_read_b128 v[226:229], v157 offset:38912
	ds_read_b128 v[230:233], v157 offset:39936
	global_load_lds_dwordx4 v[236:237], off
	v_lshl_add_u64 v[236:237], s[26:27], 0, v[132:133]
	s_mov_b32 m0, s34
	s_nop 0
	global_load_lds_dwordx4 v[236:237], off
	s_waitcnt vmcnt(8)
	s_waitcnt lgkmcnt(0)
	s_setprio 1
	s_barrier
	v_mfma_f32_16x16x32_bf16 v[124:127], v[146:149], v[188:191], v[124:127]
	v_mfma_f32_16x16x32_bf16 v[120:123], v[164:167], v[188:191], v[120:123]
	v_mfma_f32_16x16x32_bf16 v[108:111], v[146:149], v[202:205], v[108:111]
	v_mfma_f32_16x16x32_bf16 v[104:107], v[164:167], v[202:205], v[104:107]
	v_mfma_f32_16x16x32_bf16 v[92:95], v[146:149], v[218:221], v[92:95]
	v_mfma_f32_16x16x32_bf16 v[88:91], v[164:167], v[218:221], v[88:91]
	v_mfma_f32_16x16x32_bf16 v[76:79], v[146:149], v[226:229], v[76:79]
	v_mfma_f32_16x16x32_bf16 v[72:75], v[164:167], v[226:229], v[72:75]
	v_mfma_f32_16x16x32_bf16 v[124:127], v[160:163], v[198:201], v[124:127]
	v_mfma_f32_16x16x32_bf16 v[120:123], v[168:171], v[198:201], v[120:123]
	v_mfma_f32_16x16x32_bf16 v[108:111], v[160:163], v[214:217], v[108:111]
	v_mfma_f32_16x16x32_bf16 v[104:107], v[168:171], v[214:217], v[104:107]
	v_mfma_f32_16x16x32_bf16 v[92:95], v[160:163], v[222:225], v[92:95]
	v_mfma_f32_16x16x32_bf16 v[88:91], v[168:171], v[222:225], v[88:91]
	v_mfma_f32_16x16x32_bf16 v[76:79], v[160:163], v[230:233], v[76:79]
	v_mfma_f32_16x16x32_bf16 v[72:75], v[168:171], v[230:233], v[72:75]
	v_mfma_f32_16x16x32_bf16 v[116:119], v[172:175], v[188:191], v[116:119]
	v_mfma_f32_16x16x32_bf16 v[112:115], v[180:183], v[188:191], v[112:115]
	v_mfma_f32_16x16x32_bf16 v[100:103], v[172:175], v[202:205], v[100:103]
	v_mfma_f32_16x16x32_bf16 v[96:99], v[180:183], v[202:205], v[96:99]
	v_mfma_f32_16x16x32_bf16 v[84:87], v[172:175], v[218:221], v[84:87]
	v_mfma_f32_16x16x32_bf16 v[80:83], v[180:183], v[218:221], v[80:83]
	v_mfma_f32_16x16x32_bf16 v[68:71], v[172:175], v[226:229], v[68:71]
	v_mfma_f32_16x16x32_bf16 v[64:67], v[180:183], v[226:229], v[64:67]
	v_mfma_f32_16x16x32_bf16 v[116:119], v[176:179], v[198:201], v[116:119]
	v_mfma_f32_16x16x32_bf16 v[112:115], v[184:187], v[198:201], v[112:115]
	v_mfma_f32_16x16x32_bf16 v[100:103], v[176:179], v[214:217], v[100:103]
	v_mfma_f32_16x16x32_bf16 v[96:99], v[184:187], v[214:217], v[96:99]
	v_mfma_f32_16x16x32_bf16 v[84:87], v[176:179], v[222:225], v[84:87]
	v_mfma_f32_16x16x32_bf16 v[80:83], v[184:187], v[222:225], v[80:83]
	v_mfma_f32_16x16x32_bf16 v[68:71], v[176:179], v[230:233], v[68:71]
	v_mfma_f32_16x16x32_bf16 v[64:67], v[184:187], v[230:233], v[64:67]
	s_barrier
; #define PG8_STAGE(bufoff, gbase, voff) do { _Pragma("unroll") for (int _i = 0; _i < 2; ++_i) \
;         __builtin_amdgcn_global_load_lds((const unsigned*)((const char*)(gbase) + (voff)[_i]), (LAS unsigned*)(lds + (bufoff) + ldsw + _i * 8192), 16, 0, 0); } while (0)
; #define PG8_LDA(dst, b, h) do { _Pragma("unroll") for (int m = 0; m < 4; ++m) _Pragma("unroll") for (int k = 0; k < 2; ++k) dst[m][k] = *(const LAS bf16x8*)(lds + PG8_SA(b, h) + aoff + m * 2048 + k * 1024); } while (0)
; #define PG8_MMA(ai, bj, At, Bt) do { __builtin_amdgcn_s_setprio(1); _Pragma("unroll") for (int m = 0; m < 4; ++m) _Pragma("unroll") for (int n = 0; n < 2; ++n) _Pragma("unroll") for (int k = 0; k < 2; ++k) \
;         acc[ai][bj][m][n] = __builtin_amdgcn_mfma_f32_16x16x32_bf16(Bt[n][k], At[m][k], acc[ai][bj][m][n], 0, 0, 0); __builtin_amdgcn_s_setprio(0); } while (0)
; #define PG8_WAIT_V(n) asm volatile("s_waitcnt vmcnt(" #n ")" ::: "memory")
; #define PG8_WAIT_L(n) asm volatile("s_waitcnt lgkmcnt(" #n ")" ::: "memory")
; #define PG8_BAR __builtin_amdgcn_s_barrier()
; #define PG8_SCHED __builtin_amdgcn_sched_barrier(0)
; template <class Epi, bool ALIGN_EPI, bool SP2 = PG8_SP2_DEFAULT>
; __device__ __forceinline__ void gemm_phase(LAS unsigned char* lds, const Gemm g, const StaticOrder& S, const Epi& E) {
;     ...
;         for (int t = 0; t < nt; t += 2) {
;     ...
;             PG8_LDA(At, 1, 1); PG8_STAGE(PG8_SB(1, 0), b3, voffB); PG8_STAGE(PG8_SB(1, 1), b3 + hstepB, voffB); PG8_STAGE(PG8_SA(1, 0), a3, voffA);
;             PG8_WAIT_V(8); PG8_WAIT_L(0); PG8_BAR; PG8_MMA(1, 0, At, B0); PG8_MMA(1, 1, At, B1); PG8_BAR; PG8_SCHED;
;     ...
;         if constexpr (ALIGN_EPI) { if (wr == 0) PG8_BAR; }
	s_setprio 0
	s_add_i32 s26, s48, s29
	v_lshl_add_u64 v[192:193], v[192:193], 0, s[12:13]
	s_mov_b32 m0, s26
	ds_read_b128 v[188:191], v157 offset:49152
	ds_read_b128 v[198:201], v157 offset:50176
	ds_read_b128 v[202:205], v157 offset:51200
	ds_read_b128 v[214:217], v157 offset:52224
	ds_read_b128 v[218:221], v157 offset:53248
	ds_read_b128 v[222:225], v157 offset:54272
	ds_read_b128 v[226:229], v157 offset:55296
	ds_read_b128 v[230:233], v157 offset:56320
	global_load_lds_dwordx4 v[192:193], off
	s_add_i32 m0, s26, 0x2000
	s_add_u32 s24, s24, 0x100080
	v_lshl_add_u64 v[192:193], v[206:207], 0, s[12:13]
	s_addc_u32 s25, s25, 0
	s_add_i32 s26, s49, s29
	global_load_lds_dwordx4 v[192:193], off
	v_lshl_add_u64 v[192:193], s[24:25], 0, v[130:131]
	s_mov_b32 m0, s26
	s_nop 0
	global_load_lds_dwordx4 v[192:193], off
	v_lshl_add_u64 v[192:193], s[24:25], 0, v[134:135]
	s_add_i32 m0, s26, 0x2000
	s_nop 0
	global_load_lds_dwordx4 v[192:193], off
	v_lshl_add_u64 v[192:193], v[210:211], 0, s[12:13]
	s_mov_b32 m0, s36
	s_nop 0
	global_load_lds_dwordx4 v[192:193], off
	v_lshl_add_u64 v[192:193], v[234:235], 0, s[12:13]
	s_mov_b32 m0, s37
	s_nop 0
	global_load_lds_dwordx4 v[192:193], off
	s_nop 0
	s_waitcnt vmcnt(8)
	s_waitcnt lgkmcnt(0)
	s_setprio 1
	s_barrier
	v_mfma_f32_16x16x32_bf16 v[60:63], v[146:149], v[188:191], v[60:63]
	v_mfma_f32_16x16x32_bf16 v[56:59], v[164:167], v[188:191], v[56:59]
	v_mfma_f32_16x16x32_bf16 v[44:47], v[146:149], v[202:205], v[44:47]
	v_mfma_f32_16x16x32_bf16 v[40:43], v[164:167], v[202:205], v[40:43]
	v_mfma_f32_16x16x32_bf16 v[28:31], v[146:149], v[218:221], v[28:31]
	v_mfma_f32_16x16x32_bf16 v[24:27], v[164:167], v[218:221], v[24:27]
	v_mfma_f32_16x16x32_bf16 v[12:15], v[146:149], v[226:229], v[12:15]
	v_mfma_f32_16x16x32_bf16 v[8:11], v[164:167], v[226:229], v[8:11]
	v_mfma_f32_16x16x32_bf16 v[60:63], v[160:163], v[198:201], v[60:63]
	v_mfma_f32_16x16x32_bf16 v[56:59], v[168:171], v[198:201], v[56:59]
	v_mfma_f32_16x16x32_bf16 v[44:47], v[160:163], v[214:217], v[44:47]
	v_mfma_f32_16x16x32_bf16 v[40:43], v[168:171], v[214:217], v[40:43]
	v_mfma_f32_16x16x32_bf16 v[28:31], v[160:163], v[222:225], v[28:31]
	v_mfma_f32_16x16x32_bf16 v[24:27], v[168:171], v[222:225], v[24:27]
	v_mfma_f32_16x16x32_bf16 v[12:15], v[160:163], v[230:233], v[12:15]
	v_mfma_f32_16x16x32_bf16 v[8:11], v[168:171], v[230:233], v[8:11]
	v_mfma_f32_16x16x32_bf16 v[52:55], v[172:175], v[188:191], v[52:55]
	v_mfma_f32_16x16x32_bf16 v[48:51], v[180:183], v[188:191], v[48:51]
	v_mfma_f32_16x16x32_bf16 v[36:39], v[172:175], v[202:205], v[36:39]
	v_mfma_f32_16x16x32_bf16 v[32:35], v[180:183], v[202:205], v[32:35]
	v_mfma_f32_16x16x32_bf16 v[20:23], v[172:175], v[218:221], v[20:23]
	v_mfma_f32_16x16x32_bf16 v[16:19], v[180:183], v[218:221], v[16:19]
	v_mfma_f32_16x16x32_bf16 v[4:7], v[172:175], v[226:229], v[4:7]
	v_mfma_f32_16x16x32_bf16 v[0:3], v[180:183], v[226:229], v[0:3]
	v_mfma_f32_16x16x32_bf16 v[52:55], v[176:179], v[198:201], v[52:55]
	v_mfma_f32_16x16x32_bf16 v[48:51], v[184:187], v[198:201], v[48:51]
	v_mfma_f32_16x16x32_bf16 v[36:39], v[176:179], v[214:217], v[36:39]
	v_mfma_f32_16x16x32_bf16 v[32:35], v[184:187], v[214:217], v[32:35]
	v_mfma_f32_16x16x32_bf16 v[20:23], v[176:179], v[222:225], v[20:23]
	v_mfma_f32_16x16x32_bf16 v[16:19], v[184:187], v[222:225], v[16:19]
	v_mfma_f32_16x16x32_bf16 v[4:7], v[176:179], v[230:233], v[4:7]
	v_mfma_f32_16x16x32_bf16 v[0:3], v[184:187], v[230:233], v[0:3]
	s_barrier
	s_setprio 0
	s_add_i32 s47, s47, 2
	s_add_u32 s22, s22, 0x100
	s_addc_u32 s23, s23, 0
	s_add_u32 s44, s44, 0x100
	s_addc_u32 s45, s45, 0
	s_cmp_gt_u32 s47, 61
	s_cbranch_scc0 .LBB0_598
	s_and_b64 vcc, exec, s[14:15]
	s_cbranch_vccz .LBB0_601
	s_barrier

; #define PG8_STAGE(bufoff, gbase, voff) do { _Pragma("unroll") for (int _i = 0; _i < 2; ++_i) \
;         __builtin_amdgcn_global_load_lds((const unsigned*)((const char*)(gbase) + (voff)[_i]), (LAS unsigned*)(lds + (bufoff) + ldsw + _i * 8192), 16, 0, 0); } while (0)
; #define PG8_LDA(dst, b, h) do { _Pragma("unroll") for (int m = 0; m < 4; ++m) _Pragma("unroll") for (int k = 0; k < 2; ++k) dst[m][k] = *(const LAS bf16x8*)(lds + PG8_SA(b, h) + aoff + m * 2048 + k * 1024); } while (0)
; #define PG8_LDB(dst, b, h) do { _Pragma("unroll") for (int n = 0; n < 2; ++n) _Pragma("unroll") for (int k = 0; k < 2; ++k) dst[n][k] = *(const LAS bf16x8*)(lds + PG8_SB(b, h) + boff + n * 2048 + k * 1024); } while (0)
; #define PG8_MMA(ai, bj, At, Bt) do { __builtin_amdgcn_s_setprio(1); _Pragma("unroll") for (int m = 0; m < 4; ++m) _Pragma("unroll") for (int n = 0; n < 2; ++n) _Pragma("unroll") for (int k = 0; k < 2; ++k) \
;         acc[ai][bj][m][n] = __builtin_amdgcn_mfma_f32_16x16x32_bf16(Bt[n][k], At[m][k], acc[ai][bj][m][n], 0, 0, 0); __builtin_amdgcn_s_setprio(0); } while (0)
; #define PG8_WAIT_V(n) asm volatile("s_waitcnt vmcnt(" #n ")" ::: "memory")
; #define PG8_WAIT_L(n) asm volatile("s_waitcnt lgkmcnt(" #n ")" ::: "memory")
; #define PG8_BAR __builtin_amdgcn_s_barrier()
; #define PG8_SCHED __builtin_amdgcn_sched_barrier(0)
; template <class Epi, bool ALIGN_EPI, bool SP2 = PG8_SP2_DEFAULT>
; __device__ __forceinline__ void gemm_phase(LAS unsigned char* lds, const Gemm g, const StaticOrder& S, const Epi& E) {
;     ...
;             const bool last = (t == nt - 2);
;             const char* a1 = cA + (size_t)(t + 1) * kstep;
;             const char* a2 = last ? nA : cA + (size_t)(t + 2) * kstep; const char* b2 = last ? nB : cB + (size_t)(t + 2) * kstep;
;             const char* a3 = a2 + kstep; const char* b3 = b2 + kstep;
;             if constexpr (SP2) {
;             PG8_LDB(B0, 0, 0); PG8_LDB(B1, 0, 1); PG8_SCHED; PG8_LDA(At, 0, 0); PG8_STAGE(PG8_SA(1, 1), a1 + hstepA, voffA);
;             PG8_WAIT_V(8); PG8_WAIT_L(0); PG8_BAR; PG8_MMA(0, 0, At, B0); PG8_MMA(0, 1, At, B1); PG8_BAR; PG8_SCHED;
;             PG8_LDA(At, 0, 1); PG8_STAGE(PG8_SB(0, 0), b2, voffB); PG8_STAGE(PG8_SB(0, 1), b2 + hstepB, voffB); PG8_STAGE(PG8_SA(0, 0), a2, voffA);
;             PG8_WAIT_V(8); PG8_WAIT_L(0); PG8_BAR; PG8_MMA(1, 0, At, B0); PG8_MMA(1, 1, At, B1); PG8_BAR; PG8_SCHED;
.LBB0_804:
	ds_read_b128 v[144:147], v153
	ds_read_b128 v[156:159], v153 offset:1024
	ds_read_b128 v[160:163], v153 offset:2048
	ds_read_b128 v[164:167], v153 offset:3072
	ds_read_b128 v[168:171], v154
	ds_read_b128 v[172:175], v154 offset:1024
	ds_read_b128 v[176:179], v154 offset:2048
	ds_read_b128 v[180:183], v154 offset:3072
	s_add_u32 s22, s20, 0x100
	s_addc_u32 s23, s21, 0
	s_cmpk_eq_i32 s49, 0xa8
	s_cselect_b32 s27, s5, s23
	s_cselect_b32 s26, s4, s22
	s_cselect_b32 s25, s19, s48
	s_cselect_b32 s24, s18, s47
	v_lshl_add_u64 v[148:149], s[20:21], 0, v[136:137]
	s_add_i32 m0, s31, 0xc000
	ds_read_b128 v[184:187], v155
	ds_read_b128 v[188:191], v155 offset:1024
	ds_read_b128 v[192:195], v155 offset:2048
	ds_read_b128 v[196:199], v155 offset:3072
	ds_read_b128 v[200:203], v155 offset:4096
	ds_read_b128 v[204:207], v155 offset:5120
	ds_read_b128 v[208:211], v155 offset:6144
	ds_read_b128 v[212:215], v155 offset:7168
	global_load_lds_dwordx4 v[148:149], off
	v_lshl_add_u64 v[148:149], s[20:21], 0, v[138:139]
	s_add_i32 m0, s31, 0xe000
	s_nop 0
	global_load_lds_dwordx4 v[148:149], off
	s_waitcnt vmcnt(8)
	s_waitcnt lgkmcnt(0)
	s_setprio 1
	s_barrier
	v_mfma_f32_16x16x32_bf16 v[124:127], v[144:147], v[184:187], v[124:127]
	v_mfma_f32_16x16x32_bf16 v[120:123], v[160:163], v[184:187], v[120:123]
	v_mfma_f32_16x16x32_bf16 v[108:111], v[144:147], v[192:195], v[108:111]
	v_mfma_f32_16x16x32_bf16 v[104:107], v[160:163], v[192:195], v[104:107]
	v_mfma_f32_16x16x32_bf16 v[92:95], v[144:147], v[200:203], v[92:95]
	v_mfma_f32_16x16x32_bf16 v[88:91], v[160:163], v[200:203], v[88:91]
	v_mfma_f32_16x16x32_bf16 v[76:79], v[144:147], v[208:211], v[76:79]
	v_mfma_f32_16x16x32_bf16 v[72:75], v[160:163], v[208:211], v[72:75]
	v_mfma_f32_16x16x32_bf16 v[124:127], v[156:159], v[188:191], v[124:127]
	v_mfma_f32_16x16x32_bf16 v[120:123], v[164:167], v[188:191], v[120:123]
	v_mfma_f32_16x16x32_bf16 v[108:111], v[156:159], v[196:199], v[108:111]
	v_mfma_f32_16x16x32_bf16 v[104:107], v[164:167], v[196:199], v[104:107]
	v_mfma_f32_16x16x32_bf16 v[92:95], v[156:159], v[204:207], v[92:95]
	v_mfma_f32_16x16x32_bf16 v[88:91], v[164:167], v[204:207], v[88:91]
	v_mfma_f32_16x16x32_bf16 v[76:79], v[156:159], v[212:215], v[76:79]
	v_mfma_f32_16x16x32_bf16 v[72:75], v[164:167], v[212:215], v[72:75]
	v_mfma_f32_16x16x32_bf16 v[116:119], v[168:171], v[184:187], v[116:119]
	v_mfma_f32_16x16x32_bf16 v[112:115], v[176:179], v[184:187], v[112:115]
	v_mfma_f32_16x16x32_bf16 v[100:103], v[168:171], v[192:195], v[100:103]
	v_mfma_f32_16x16x32_bf16 v[96:99], v[176:179], v[192:195], v[96:99]
	v_mfma_f32_16x16x32_bf16 v[84:87], v[168:171], v[200:203], v[84:87]
	v_mfma_f32_16x16x32_bf16 v[80:83], v[176:179], v[200:203], v[80:83]
	v_mfma_f32_16x16x32_bf16 v[68:71], v[168:171], v[208:211], v[68:71]
	v_mfma_f32_16x16x32_bf16 v[64:67], v[176:179], v[208:211], v[64:67]
	v_mfma_f32_16x16x32_bf16 v[116:119], v[172:175], v[188:191], v[116:119]
	v_mfma_f32_16x16x32_bf16 v[112:115], v[180:183], v[188:191], v[112:115]
	v_mfma_f32_16x16x32_bf16 v[100:103], v[172:175], v[196:199], v[100:103]
	v_mfma_f32_16x16x32_bf16 v[96:99], v[180:183], v[196:199], v[96:99]
	v_mfma_f32_16x16x32_bf16 v[84:87], v[172:175], v[204:207], v[84:87]
	v_mfma_f32_16x16x32_bf16 v[80:83], v[180:183], v[204:207], v[80:83]
	v_mfma_f32_16x16x32_bf16 v[68:71], v[172:175], v[212:215], v[68:71]
	v_mfma_f32_16x16x32_bf16 v[64:67], v[180:183], v[212:215], v[64:67]
	s_barrier
	s_setprio 0
	s_add_i32 s20, s40, s28
	v_lshl_add_u64 v[148:149], s[24:25], 0, v[130:131]
	s_mov_b32 m0, s20
	ds_read_b128 v[184:187], v155 offset:16384
	ds_read_b128 v[188:191], v155 offset:17408
	ds_read_b128 v[192:195], v155 offset:18432
	ds_read_b128 v[196:199], v155 offset:19456
	ds_read_b128 v[200:203], v155 offset:20480
	ds_read_b128 v[204:207], v155 offset:21504
	ds_read_b128 v[208:211], v155 offset:22528
	ds_read_b128 v[212:215], v155 offset:23552
	global_load_lds_dwordx4 v[148:149], off
	s_add_i32 m0, s20, 0x2000
	s_add_u32 s20, s24, 0x2b0000
	v_lshl_add_u64 v[216:217], s[24:25], 0, v[134:135]
	s_addc_u32 s21, s25, 0
	s_add_i32 s50, s41, s28
	global_load_lds_dwordx4 v[216:217], off
	v_lshl_add_u64 v[218:219], s[20:21], 0, v[130:131]
	s_mov_b32 m0, s50
	v_lshl_add_u64 v[220:221], s[26:27], 0, v[132:133]
	global_load_lds_dwordx4 v[218:219], off
	v_lshl_add_u64 v[218:219], s[20:21], 0, v[134:135]
	s_add_i32 m0, s50, 0x2000
	s_nop 0
	global_load_lds_dwordx4 v[218:219], off
	v_lshl_add_u64 v[218:219], s[26:27], 0, v[128:129]
	s_mov_b32 m0, s31
	s_nop 0
	global_load_lds_dwordx4 v[218:219], off
	s_mov_b32 m0, s33
	s_nop 0
	global_load_lds_dwordx4 v[220:221], off
	s_waitcnt vmcnt(8)
	s_waitcnt lgkmcnt(0)
	s_setprio 1
	s_barrier
; #define PG8_STAGE(bufoff, gbase, voff) do { _Pragma("unroll") for (int _i = 0; _i < 2; ++_i) \
;         __builtin_amdgcn_global_load_lds((const unsigned*)((const char*)(gbase) + (voff)[_i]), (LAS unsigned*)(lds + (bufoff) + ldsw + _i * 8192), 16, 0, 0); } while (0)
; #define PG8_LDA(dst, b, h) do { _Pragma("unroll") for (int m = 0; m < 4; ++m) _Pragma("unroll") for (int k = 0; k < 2; ++k) dst[m][k] = *(const LAS bf16x8*)(lds + PG8_SA(b, h) + aoff + m * 2048 + k * 1024); } while (0)
; #define PG8_LDB(dst, b, h) do { _Pragma("unroll") for (int n = 0; n < 2; ++n) _Pragma("unroll") for (int k = 0; k < 2; ++k) dst[n][k] = *(const LAS bf16x8*)(lds + PG8_SB(b, h) + boff + n * 2048 + k * 1024); } while (0)
; #define PG8_MMA(ai, bj, At, Bt) do { __builtin_amdgcn_s_setprio(1); _Pragma("unroll") for (int m = 0; m < 4; ++m) _Pragma("unroll") for (int n = 0; n < 2; ++n) _Pragma("unroll") for (int k = 0; k < 2; ++k) \
;         acc[ai][bj][m][n] = __builtin_amdgcn_mfma_f32_16x16x32_bf16(Bt[n][k], At[m][k], acc[ai][bj][m][n], 0, 0, 0); __builtin_amdgcn_s_setprio(0); } while (0)
; #define PG8_WAIT_V(n) asm volatile("s_waitcnt vmcnt(" #n ")" ::: "memory")
; #define PG8_WAIT_L(n) asm volatile("s_waitcnt lgkmcnt(" #n ")" ::: "memory")
; #define PG8_BAR __builtin_amdgcn_s_barrier()
; #define PG8_SCHED __builtin_amdgcn_sched_barrier(0)
; template <class Epi, bool ALIGN_EPI, bool SP2 = PG8_SP2_DEFAULT>
; __device__ __forceinline__ void gemm_phase(LAS unsigned char* lds, const Gemm g, const StaticOrder& S, const Epi& E) {
;     ...
;             PG8_WAIT_V(8); PG8_WAIT_L(0); PG8_BAR; PG8_MMA(1, 0, At, B0); PG8_MMA(1, 1, At, B1); PG8_BAR; PG8_SCHED;
;             PG8_LDB(B0, 1, 0); PG8_LDB(B1, 1, 1); PG8_SCHED; PG8_LDA(At, 1, 0); PG8_STAGE(PG8_SA(0, 1), a2 + hstepA, voffA);
;             PG8_WAIT_V(8); PG8_WAIT_L(0); PG8_BAR; PG8_MMA(0, 0, At, B0); PG8_MMA(0, 1, At, B1); PG8_BAR; PG8_SCHED;
	v_mfma_f32_16x16x32_bf16 v[60:63], v[144:147], v[184:187], v[60:63]
	v_mfma_f32_16x16x32_bf16 v[56:59], v[160:163], v[184:187], v[56:59]
	v_mfma_f32_16x16x32_bf16 v[44:47], v[144:147], v[192:195], v[44:47]
	v_mfma_f32_16x16x32_bf16 v[40:43], v[160:163], v[192:195], v[40:43]
	v_mfma_f32_16x16x32_bf16 v[28:31], v[144:147], v[200:203], v[28:31]
	v_mfma_f32_16x16x32_bf16 v[24:27], v[160:163], v[200:203], v[24:27]
	v_mfma_f32_16x16x32_bf16 v[12:15], v[144:147], v[208:211], v[12:15]
	v_mfma_f32_16x16x32_bf16 v[8:11], v[160:163], v[208:211], v[8:11]
	v_mfma_f32_16x16x32_bf16 v[60:63], v[156:159], v[188:191], v[60:63]
	v_mfma_f32_16x16x32_bf16 v[56:59], v[164:167], v[188:191], v[56:59]
	v_mfma_f32_16x16x32_bf16 v[44:47], v[156:159], v[196:199], v[44:47]
	v_mfma_f32_16x16x32_bf16 v[40:43], v[164:167], v[196:199], v[40:43]
	v_mfma_f32_16x16x32_bf16 v[28:31], v[156:159], v[204:207], v[28:31]
	v_mfma_f32_16x16x32_bf16 v[24:27], v[164:167], v[204:207], v[24:27]
	v_mfma_f32_16x16x32_bf16 v[12:15], v[156:159], v[212:215], v[12:15]
	v_mfma_f32_16x16x32_bf16 v[8:11], v[164:167], v[212:215], v[8:11]
	v_mfma_f32_16x16x32_bf16 v[52:55], v[168:171], v[184:187], v[52:55]
	v_mfma_f32_16x16x32_bf16 v[48:51], v[176:179], v[184:187], v[48:51]
	v_mfma_f32_16x16x32_bf16 v[36:39], v[168:171], v[192:195], v[36:39]
	v_mfma_f32_16x16x32_bf16 v[32:35], v[176:179], v[192:195], v[32:35]
	v_mfma_f32_16x16x32_bf16 v[20:23], v[168:171], v[200:203], v[20:23]
	v_mfma_f32_16x16x32_bf16 v[16:19], v[176:179], v[200:203], v[16:19]
	v_mfma_f32_16x16x32_bf16 v[4:7], v[168:171], v[208:211], v[4:7]
	v_mfma_f32_16x16x32_bf16 v[0:3], v[176:179], v[208:211], v[0:3]
	v_mfma_f32_16x16x32_bf16 v[52:55], v[172:175], v[188:191], v[52:55]
	v_mfma_f32_16x16x32_bf16 v[48:51], v[180:183], v[188:191], v[48:51]
	v_mfma_f32_16x16x32_bf16 v[36:39], v[172:175], v[196:199], v[36:39]
	v_mfma_f32_16x16x32_bf16 v[32:35], v[180:183], v[196:199], v[32:35]
	v_mfma_f32_16x16x32_bf16 v[20:23], v[172:175], v[204:207], v[20:23]
	v_mfma_f32_16x16x32_bf16 v[16:19], v[180:183], v[204:207], v[16:19]
	v_mfma_f32_16x16x32_bf16 v[4:7], v[172:175], v[212:215], v[4:7]
	v_mfma_f32_16x16x32_bf16 v[0:3], v[180:183], v[212:215], v[0:3]
	s_barrier
	s_setprio 0
	s_add_i32 s50, 0, 0x18000
	s_add_i32 s51, 0, 0x1c000
	v_add_u32_e32 v164, s50, v151
	v_add_u32_e32 v180, s51, v151
	ds_read_b128 v[144:147], v164
	ds_read_b128 v[156:159], v164 offset:1024
	ds_read_b128 v[160:163], v164 offset:2048
	ds_read_b128 v[164:167], v164 offset:3072
	ds_read_b128 v[168:171], v180
	ds_read_b128 v[172:175], v180 offset:1024
	ds_read_b128 v[176:179], v180 offset:2048
	ds_read_b128 v[180:183], v180 offset:3072
	s_add_u32 s20, s26, 0x2b0000
	s_addc_u32 s21, s27, 0
	s_mov_b32 m0, s34
	v_lshl_add_u64 v[222:223], s[20:21], 0, v[128:129]
	ds_read_b128 v[184:187], v155 offset:32768
	ds_read_b128 v[188:191], v155 offset:33792
	ds_read_b128 v[192:195], v155 offset:34816
	ds_read_b128 v[196:199], v155 offset:35840
	ds_read_b128 v[200:203], v155 offset:36864
	ds_read_b128 v[204:207], v155 offset:37888
	ds_read_b128 v[208:211], v155 offset:38912
	ds_read_b128 v[212:215], v155 offset:39936
	global_load_lds_dwordx4 v[222:223], off
	v_lshl_add_u64 v[222:223], s[20:21], 0, v[132:133]
	s_mov_b32 m0, s35
	s_nop 0
	global_load_lds_dwordx4 v[222:223], off
	s_waitcnt vmcnt(8)
	s_waitcnt lgkmcnt(0)
	s_setprio 1
	s_barrier
	v_mfma_f32_16x16x32_bf16 v[124:127], v[144:147], v[184:187], v[124:127]
	v_mfma_f32_16x16x32_bf16 v[120:123], v[160:163], v[184:187], v[120:123]
	v_mfma_f32_16x16x32_bf16 v[108:111], v[144:147], v[192:195], v[108:111]
	v_mfma_f32_16x16x32_bf16 v[104:107], v[160:163], v[192:195], v[104:107]
	v_mfma_f32_16x16x32_bf16 v[92:95], v[144:147], v[200:203], v[92:95]
	v_mfma_f32_16x16x32_bf16 v[88:91], v[160:163], v[200:203], v[88:91]
	v_mfma_f32_16x16x32_bf16 v[76:79], v[144:147], v[208:211], v[76:79]
	v_mfma_f32_16x16x32_bf16 v[72:75], v[160:163], v[208:211], v[72:75]
	v_mfma_f32_16x16x32_bf16 v[124:127], v[156:159], v[188:191], v[124:127]
	v_mfma_f32_16x16x32_bf16 v[120:123], v[164:167], v[188:191], v[120:123]
	v_mfma_f32_16x16x32_bf16 v[108:111], v[156:159], v[196:199], v[108:111]
	v_mfma_f32_16x16x32_bf16 v[104:107], v[164:167], v[196:199], v[104:107]
	v_mfma_f32_16x16x32_bf16 v[92:95], v[156:159], v[204:207], v[92:95]
	v_mfma_f32_16x16x32_bf16 v[88:91], v[164:167], v[204:207], v[88:91]
	v_mfma_f32_16x16x32_bf16 v[76:79], v[156:159], v[212:215], v[76:79]
	v_mfma_f32_16x16x32_bf16 v[72:75], v[164:167], v[212:215], v[72:75]
	v_mfma_f32_16x16x32_bf16 v[116:119], v[168:171], v[184:187], v[116:119]
	v_mfma_f32_16x16x32_bf16 v[112:115], v[176:179], v[184:187], v[112:115]
	v_mfma_f32_16x16x32_bf16 v[100:103], v[168:171], v[192:195], v[100:103]
	v_mfma_f32_16x16x32_bf16 v[96:99], v[176:179], v[192:195], v[96:99]
	v_mfma_f32_16x16x32_bf16 v[84:87], v[168:171], v[200:203], v[84:87]
	v_mfma_f32_16x16x32_bf16 v[80:83], v[176:179], v[200:203], v[80:83]
	v_mfma_f32_16x16x32_bf16 v[68:71], v[168:171], v[208:211], v[68:71]
	v_mfma_f32_16x16x32_bf16 v[64:67], v[176:179], v[208:211], v[64:67]
	v_mfma_f32_16x16x32_bf16 v[116:119], v[172:175], v[188:191], v[116:119]
	v_mfma_f32_16x16x32_bf16 v[112:115], v[180:183], v[188:191], v[112:115]
	v_mfma_f32_16x16x32_bf16 v[100:103], v[172:175], v[196:199], v[100:103]
	v_mfma_f32_16x16x32_bf16 v[96:99], v[180:183], v[196:199], v[96:99]
	v_mfma_f32_16x16x32_bf16 v[84:87], v[172:175], v[204:207], v[84:87]
	v_mfma_f32_16x16x32_bf16 v[80:83], v[180:183], v[204:207], v[80:83]
	v_mfma_f32_16x16x32_bf16 v[68:71], v[172:175], v[212:215], v[68:71]
	v_mfma_f32_16x16x32_bf16 v[64:67], v[180:183], v[212:215], v[64:67]
	s_barrier
; #define PG8_STAGE(bufoff, gbase, voff) do { _Pragma("unroll") for (int _i = 0; _i < 2; ++_i) \
;         __builtin_amdgcn_global_load_lds((const unsigned*)((const char*)(gbase) + (voff)[_i]), (LAS unsigned*)(lds + (bufoff) + ldsw + _i * 8192), 16, 0, 0); } while (0)
; #define PG8_LDA(dst, b, h) do { _Pragma("unroll") for (int m = 0; m < 4; ++m) _Pragma("unroll") for (int k = 0; k < 2; ++k) dst[m][k] = *(const LAS bf16x8*)(lds + PG8_SA(b, h) + aoff + m * 2048 + k * 1024); } while (0)
; #define PG8_MMA(ai, bj, At, Bt) do { __builtin_amdgcn_s_setprio(1); _Pragma("unroll") for (int m = 0; m < 4; ++m) _Pragma("unroll") for (int n = 0; n < 2; ++n) _Pragma("unroll") for (int k = 0; k < 2; ++k) \
;         acc[ai][bj][m][n] = __builtin_amdgcn_mfma_f32_16x16x32_bf16(Bt[n][k], At[m][k], acc[ai][bj][m][n], 0, 0, 0); __builtin_amdgcn_s_setprio(0); } while (0)
; #define PG8_WAIT_V(n) asm volatile("s_waitcnt vmcnt(" #n ")" ::: "memory")
; #define PG8_WAIT_L(n) asm volatile("s_waitcnt lgkmcnt(" #n ")" ::: "memory")
; #define PG8_BAR __builtin_amdgcn_s_barrier()
; #define PG8_SCHED __builtin_amdgcn_sched_barrier(0)
; template <class Epi, bool ALIGN_EPI, bool SP2 = PG8_SP2_DEFAULT>
; __device__ __forceinline__ void gemm_phase(LAS unsigned char* lds, const Gemm g, const StaticOrder& S, const Epi& E) {
;     ...
;         for (int t = 0; t < nt; t += 2) {
;             const bool last = (t == nt - 2);
;     ...
;             PG8_LDA(At, 1, 1); PG8_STAGE(PG8_SB(1, 0), b3, voffB); PG8_STAGE(PG8_SB(1, 1), b3 + hstepB, voffB); PG8_STAGE(PG8_SA(1, 0), a3, voffA);
;             PG8_WAIT_V(8); PG8_WAIT_L(0); PG8_BAR; PG8_MMA(1, 0, At, B0); PG8_MMA(1, 1, At, B1); PG8_BAR; PG8_SCHED;
	s_setprio 0
	s_add_i32 s20, s50, s28
	v_lshl_add_u64 v[148:149], v[148:149], 0, s[6:7]
	s_mov_b32 m0, s20
	ds_read_b128 v[184:187], v155 offset:49152
	ds_read_b128 v[188:191], v155 offset:50176
	ds_read_b128 v[192:195], v155 offset:51200
	ds_read_b128 v[196:199], v155 offset:52224
	ds_read_b128 v[200:203], v155 offset:53248
	ds_read_b128 v[204:207], v155 offset:54272
	ds_read_b128 v[208:211], v155 offset:55296
	ds_read_b128 v[212:215], v155 offset:56320
	global_load_lds_dwordx4 v[148:149], off
	s_add_i32 m0, s20, 0x2000
	s_add_u32 s20, s24, 0x2b0080
	v_lshl_add_u64 v[148:149], v[216:217], 0, s[6:7]
	s_addc_u32 s21, s25, 0
	s_add_i32 s24, s51, s28
	global_load_lds_dwordx4 v[148:149], off
	v_lshl_add_u64 v[148:149], s[20:21], 0, v[130:131]
	s_mov_b32 m0, s24
	s_nop 0
	global_load_lds_dwordx4 v[148:149], off
	v_lshl_add_u64 v[148:149], s[20:21], 0, v[134:135]
	s_add_i32 m0, s24, 0x2000
	s_nop 0
	global_load_lds_dwordx4 v[148:149], off
	v_lshl_add_u64 v[148:149], v[218:219], 0, s[6:7]
	s_mov_b32 m0, s37
	s_nop 0
	global_load_lds_dwordx4 v[148:149], off
	v_lshl_add_u64 v[148:149], v[220:221], 0, s[6:7]
	s_mov_b32 m0, s38
	s_nop 0
	global_load_lds_dwordx4 v[148:149], off
	s_nop 0
	s_waitcnt vmcnt(8)
	s_waitcnt lgkmcnt(0)
	s_setprio 1
	s_barrier
	v_mfma_f32_16x16x32_bf16 v[60:63], v[144:147], v[184:187], v[60:63]
	v_mfma_f32_16x16x32_bf16 v[56:59], v[160:163], v[184:187], v[56:59]
	v_mfma_f32_16x16x32_bf16 v[44:47], v[144:147], v[192:195], v[44:47]
	v_mfma_f32_16x16x32_bf16 v[40:43], v[160:163], v[192:195], v[40:43]
	v_mfma_f32_16x16x32_bf16 v[28:31], v[144:147], v[200:203], v[28:31]
	v_mfma_f32_16x16x32_bf16 v[24:27], v[160:163], v[200:203], v[24:27]
	v_mfma_f32_16x16x32_bf16 v[12:15], v[144:147], v[208:211], v[12:15]
	v_mfma_f32_16x16x32_bf16 v[8:11], v[160:163], v[208:211], v[8:11]
	v_mfma_f32_16x16x32_bf16 v[60:63], v[156:159], v[188:191], v[60:63]
	v_mfma_f32_16x16x32_bf16 v[56:59], v[164:167], v[188:191], v[56:59]
	v_mfma_f32_16x16x32_bf16 v[44:47], v[156:159], v[196:199], v[44:47]
	v_mfma_f32_16x16x32_bf16 v[40:43], v[164:167], v[196:199], v[40:43]
	v_mfma_f32_16x16x32_bf16 v[28:31], v[156:159], v[204:207], v[28:31]
	v_mfma_f32_16x16x32_bf16 v[24:27], v[164:167], v[204:207], v[24:27]
	v_mfma_f32_16x16x32_bf16 v[12:15], v[156:159], v[212:215], v[12:15]
	v_mfma_f32_16x16x32_bf16 v[8:11], v[164:167], v[212:215], v[8:11]
	v_mfma_f32_16x16x32_bf16 v[52:55], v[168:171], v[184:187], v[52:55]
	v_mfma_f32_16x16x32_bf16 v[48:51], v[176:179], v[184:187], v[48:51]
	v_mfma_f32_16x16x32_bf16 v[36:39], v[168:171], v[192:195], v[36:39]
	v_mfma_f32_16x16x32_bf16 v[32:35], v[176:179], v[192:195], v[32:35]
	v_mfma_f32_16x16x32_bf16 v[20:23], v[168:171], v[200:203], v[20:23]
	v_mfma_f32_16x16x32_bf16 v[16:19], v[176:179], v[200:203], v[16:19]
	v_mfma_f32_16x16x32_bf16 v[4:7], v[168:171], v[208:211], v[4:7]
	v_mfma_f32_16x16x32_bf16 v[0:3], v[176:179], v[208:211], v[0:3]
	v_mfma_f32_16x16x32_bf16 v[52:55], v[172:175], v[188:191], v[52:55]
	v_mfma_f32_16x16x32_bf16 v[48:51], v[180:183], v[188:191], v[48:51]
	v_mfma_f32_16x16x32_bf16 v[36:39], v[172:175], v[196:199], v[36:39]
	v_mfma_f32_16x16x32_bf16 v[32:35], v[180:183], v[196:199], v[32:35]
	v_mfma_f32_16x16x32_bf16 v[20:23], v[172:175], v[204:207], v[20:23]
	v_mfma_f32_16x16x32_bf16 v[16:19], v[180:183], v[204:207], v[16:19]
	v_mfma_f32_16x16x32_bf16 v[4:7], v[172:175], v[212:215], v[4:7]
	v_mfma_f32_16x16x32_bf16 v[0:3], v[180:183], v[212:215], v[0:3]
	s_barrier
	s_setprio 0
	s_add_i32 s49, s49, 2
	s_add_u32 s47, s47, 0x100
	s_addc_u32 s48, s48, 0
	s_cmpk_gt_u32 s49, 0xa9
	s_mov_b64 s[20:21], s[22:23]
	s_cbranch_scc0 .LBB0_804
	s_and_b64 vcc, exec, s[8:9]
	s_cbranch_vccz .LBB0_807
	s_barrier
